# batched the serialized loads of the forget-gate cumsum, final norm gain (hoisted out of row loop) and prologue loops (silu(c), compression-weight transposes, pos@w1)
# speedup vs baseline: 1.0076x; 1.0019x over previous
; #define LAS __attribute__((address_space(3)))
; __device__ __forceinline__ void p0_mod(const float* c, const float* ada_w, const float* ada_b, float* MOD, LAS unsigned char* lds, int bid, int G, int tid, int wave, int lane) {
;     LAS float* cact = (LAS float*)lds;
;     LAS f32x4* red = (LAS f32x4*)(lds + 16384);
;     for (int i = tid; i < BATCH * DM; i += NWAVES * 64) { const float x = c[i]; cact[i] = x / (1.f + __expf(-x)); }
;     __syncthreads();
.LBB0_162:
	flat_load_dword v146, v[2:3]
	v_lshl_add_u64 v[2:3], v[2:3], 0, s[20:21]
	flat_load_dword v147, v[2:3]
	v_lshl_add_u64 v[2:3], v[2:3], 0, s[20:21]
	flat_load_dword v148, v[2:3]
	v_lshl_add_u64 v[2:3], v[2:3], 0, s[20:21]
	flat_load_dword v149, v[2:3]
	v_lshl_add_u64 v[2:3], v[2:3], 0, s[20:21]
	flat_load_dword v150, v[2:3]
	v_lshl_add_u64 v[2:3], v[2:3], 0, s[20:21]
	flat_load_dword v151, v[2:3]
	v_lshl_add_u64 v[2:3], v[2:3], 0, s[20:21]
	flat_load_dword v152, v[2:3]
	v_lshl_add_u64 v[2:3], v[2:3], 0, s[20:21]
	flat_load_dword v153, v[2:3]
	s_waitcnt vmcnt(0) lgkmcnt(0)
	v_mul_f32_e32 v7, 0xbfb8aa3b, v146
	v_exp_f32_e32 v7, v7
	s_nop 0
	v_add_f32_e32 v7, 1.0, v7
	v_div_scale_f32 v8, s[28:29], v7, v7, v146
	v_rcp_f32_e32 v9, v8
	v_div_scale_f32 v11, vcc, v146, v7, v146
	v_fma_f32 v12, -v8, v9, 1.0
	v_fmac_f32_e32 v9, v12, v9
	v_mul_f32_e32 v12, v11, v9
	v_fma_f32 v13, -v8, v12, v11
	v_fmac_f32_e32 v12, v13, v9
	v_fma_f32 v8, -v8, v12, v11
	v_div_fmas_f32 v8, v8, v9, v12
	v_div_fixup_f32 v6, v8, v7, v146
	ds_write_b32 v5, v6
	v_mul_f32_e32 v7, 0xbfb8aa3b, v147
	v_exp_f32_e32 v7, v7
	s_nop 0
	v_add_f32_e32 v7, 1.0, v7
	v_div_scale_f32 v8, s[28:29], v7, v7, v147
	v_rcp_f32_e32 v9, v8
	v_div_scale_f32 v11, vcc, v147, v7, v147
	v_fma_f32 v12, -v8, v9, 1.0
	v_fmac_f32_e32 v9, v12, v9
	v_mul_f32_e32 v12, v11, v9
	v_fma_f32 v13, -v8, v12, v11
	v_fmac_f32_e32 v12, v13, v9
	v_fma_f32 v8, -v8, v12, v11
	v_div_fmas_f32 v8, v8, v9, v12
	v_div_fixup_f32 v6, v8, v7, v147
	ds_write_b32 v5, v6 offset:2048
	v_mul_f32_e32 v7, 0xbfb8aa3b, v148
	v_exp_f32_e32 v7, v7
	s_nop 0
	v_add_f32_e32 v7, 1.0, v7
	v_div_scale_f32 v8, s[28:29], v7, v7, v148
	v_rcp_f32_e32 v9, v8
	v_div_scale_f32 v11, vcc, v148, v7, v148
	v_fma_f32 v12, -v8, v9, 1.0
	v_fmac_f32_e32 v9, v12, v9
	v_mul_f32_e32 v12, v11, v9
	v_fma_f32 v13, -v8, v12, v11
	v_fmac_f32_e32 v12, v13, v9
	v_fma_f32 v8, -v8, v12, v11
	v_div_fmas_f32 v8, v8, v9, v12
	v_div_fixup_f32 v6, v8, v7, v148
	ds_write_b32 v5, v6 offset:4096
	v_mul_f32_e32 v7, 0xbfb8aa3b, v149
	v_exp_f32_e32 v7, v7
	s_nop 0
	v_add_f32_e32 v7, 1.0, v7
	v_div_scale_f32 v8, s[28:29], v7, v7, v149
	v_rcp_f32_e32 v9, v8
	v_div_scale_f32 v11, vcc, v149, v7, v149
	v_fma_f32 v12, -v8, v9, 1.0
	v_fmac_f32_e32 v9, v12, v9
	v_mul_f32_e32 v12, v11, v9
	v_fma_f32 v13, -v8, v12, v11
	v_fmac_f32_e32 v12, v13, v9
	v_fma_f32 v8, -v8, v12, v11
	v_div_fmas_f32 v8, v8, v9, v12
	v_div_fixup_f32 v6, v8, v7, v149
	ds_write_b32 v5, v6 offset:6144
	v_mul_f32_e32 v7, 0xbfb8aa3b, v150
	v_exp_f32_e32 v7, v7
	s_nop 0
	v_add_f32_e32 v7, 1.0, v7
	v_div_scale_f32 v8, s[28:29], v7, v7, v150
	v_rcp_f32_e32 v9, v8
	v_div_scale_f32 v11, vcc, v150, v7, v150
	v_fma_f32 v12, -v8, v9, 1.0
	v_fmac_f32_e32 v9, v12, v9
	v_mul_f32_e32 v12, v11, v9
	v_fma_f32 v13, -v8, v12, v11
	v_fmac_f32_e32 v12, v13, v9
	v_fma_f32 v8, -v8, v12, v11
	v_div_fmas_f32 v8, v8, v9, v12
	v_div_fixup_f32 v6, v8, v7, v150
	ds_write_b32 v5, v6 offset:8192
	v_mul_f32_e32 v7, 0xbfb8aa3b, v151
	v_exp_f32_e32 v7, v7
	s_nop 0
	v_add_f32_e32 v7, 1.0, v7
	v_div_scale_f32 v8, s[28:29], v7, v7, v151
	v_rcp_f32_e32 v9, v8
	v_div_scale_f32 v11, vcc, v151, v7, v151
	v_fma_f32 v12, -v8, v9, 1.0
	v_fmac_f32_e32 v9, v12, v9
	v_mul_f32_e32 v12, v11, v9
	v_fma_f32 v13, -v8, v12, v11
	v_fmac_f32_e32 v12, v13, v9
	v_fma_f32 v8, -v8, v12, v11
	v_div_fmas_f32 v8, v8, v9, v12
	v_div_fixup_f32 v6, v8, v7, v151
	ds_write_b32 v5, v6 offset:10240
	v_mul_f32_e32 v7, 0xbfb8aa3b, v152
	v_exp_f32_e32 v7, v7
	s_nop 0
	v_add_f32_e32 v7, 1.0, v7
	v_div_scale_f32 v8, s[28:29], v7, v7, v152
	v_rcp_f32_e32 v9, v8
	v_div_scale_f32 v11, vcc, v152, v7, v152
	v_fma_f32 v12, -v8, v9, 1.0
	v_fmac_f32_e32 v9, v12, v9
	v_mul_f32_e32 v12, v11, v9
	v_fma_f32 v13, -v8, v12, v11
	v_fmac_f32_e32 v12, v13, v9
	v_fma_f32 v8, -v8, v12, v11
	v_div_fmas_f32 v8, v8, v9, v12
	v_div_fixup_f32 v6, v8, v7, v152
	ds_write_b32 v5, v6 offset:12288
	v_mul_f32_e32 v7, 0xbfb8aa3b, v153
	v_exp_f32_e32 v7, v7
	s_nop 0
	v_add_f32_e32 v7, 1.0, v7
	v_div_scale_f32 v8, s[28:29], v7, v7, v153
	v_rcp_f32_e32 v9, v8
	v_div_scale_f32 v11, vcc, v153, v7, v153
	v_fma_f32 v12, -v8, v9, 1.0
	v_fmac_f32_e32 v9, v12, v9
	v_mul_f32_e32 v12, v11, v9
	v_fma_f32 v13, -v8, v12, v11
	v_fmac_f32_e32 v12, v13, v9
	v_fma_f32 v8, -v8, v12, v11
	v_div_fmas_f32 v8, v8, v9, v12
	v_div_fixup_f32 v6, v8, v7, v153
	ds_write_b32 v5, v6 offset:14336

; #define LAS __attribute__((address_space(3)))
; #define LDS_WAIT() asm volatile("s_waitcnt lgkmcnt(0)" ::: "memory")
; __device__ __forceinline__ unsigned pk2(float lo, float hi) { pk2_f2_t v = {lo, hi}; pk2_b2_t b = __builtin_convertvector(v, pk2_b2_t); return __builtin_bit_cast(unsigned, b); }
; __device__ __forceinline__ void tr_item(const float* W, int K, int N, int srccol, bf16* WT, int destrow0, int k0, LAS float* scr, int lane) {
; #pragma unroll 8
;     for (int i = 0; i < 32; ++i) { const int kk = 2 * i + (lane >> 5); scr[kk * 33 + (lane & 31)] = srccol >= 0 ? W[(size_t)(k0 + kk) * N + srccol] : 0.f; }
;     LDS_WAIT(); asm volatile("" ::: "memory");
;     const int c = lane & 7;
; #pragma unroll
;     for (int j = 0; j < 4; ++j) { const int n = (lane >> 3) + 8 * j; const LAS float* s = scr + (8 * c) * 33 + n;
;         v4u o; o.x = pk2(s[0 * 33], s[1 * 33]); o.y = pk2(s[2 * 33], s[3 * 33]); o.z = pk2(s[4 * 33], s[5 * 33]); o.w = pk2(s[6 * 33], s[7 * 33]);
;         *(v4u*)(WT + (size_t)(destrow0 + n) * K + k0 + 8 * c) = o; }
;     LDS_WAIT(); asm volatile("" ::: "memory");
; }
; __device__ __forceinline__ void p0_cmpw(const float* w1, const float* w2, const float* pos, unsigned char* ws, LAS unsigned char* lds, int gw, int NGW, int bid, int G, int wave, int lane) {
;     ...
;         else { const int r = it - DEPTH * 2 * 64, lk = r >> 1, nb = r & 1;
;             tr_item(w2 + (size_t)lk * 64 * 64, 64, 64, nb * 32 + (lane & 31), (bf16*)(ws + WS_W2T) + (size_t)lk * 64 * 64, nb * 32, 0, scr, lane); }
.LBB0_177:
	v_lshl_add_u64 v[38:39], v[22:23], 0, s[22:23]
	flat_load_dword v146, v[38:39]
	v_lshl_add_u64 v[38:39], v[20:21], 0, s[22:23]
	flat_load_dword v147, v[38:39]
	v_lshl_add_u64 v[38:39], v[18:19], 0, s[22:23]
	flat_load_dword v148, v[38:39]
	v_lshl_add_u64 v[38:39], v[16:17], 0, s[22:23]
	flat_load_dword v149, v[38:39]
	v_lshl_add_u64 v[38:39], v[14:15], 0, s[22:23]
	flat_load_dword v150, v[38:39]
	v_lshl_add_u64 v[38:39], v[12:13], 0, s[22:23]
	flat_load_dword v151, v[38:39]
	v_lshl_add_u64 v[38:39], v[10:11], 0, s[22:23]
	flat_load_dword v152, v[38:39]
	v_lshl_add_u64 v[38:39], v[8:9], 0, s[22:23]
	flat_load_dword v153, v[38:39]
	s_add_u32 s22, s22, 0x1000
	s_addc_u32 s23, s23, 0
	v_lshl_add_u64 v[38:39], v[22:23], 0, s[22:23]
	flat_load_dword v154, v[38:39]
	v_lshl_add_u64 v[38:39], v[20:21], 0, s[22:23]
	flat_load_dword v155, v[38:39]
	v_lshl_add_u64 v[38:39], v[18:19], 0, s[22:23]
	flat_load_dword v156, v[38:39]
	v_lshl_add_u64 v[38:39], v[16:17], 0, s[22:23]
	flat_load_dword v157, v[38:39]
	v_lshl_add_u64 v[38:39], v[14:15], 0, s[22:23]
	flat_load_dword v158, v[38:39]
	v_lshl_add_u64 v[38:39], v[12:13], 0, s[22:23]
	flat_load_dword v159, v[38:39]
	v_lshl_add_u64 v[38:39], v[10:11], 0, s[22:23]
	flat_load_dword v160, v[38:39]
	v_lshl_add_u64 v[38:39], v[8:9], 0, s[22:23]
	flat_load_dword v161, v[38:39]
	s_add_u32 s22, s22, 0x1000
	s_addc_u32 s23, s23, 0
	v_lshl_add_u64 v[38:39], v[22:23], 0, s[22:23]
	flat_load_dword v162, v[38:39]
	v_lshl_add_u64 v[38:39], v[20:21], 0, s[22:23]
	flat_load_dword v163, v[38:39]
	v_lshl_add_u64 v[38:39], v[18:19], 0, s[22:23]
	flat_load_dword v164, v[38:39]
	v_lshl_add_u64 v[38:39], v[16:17], 0, s[22:23]
	flat_load_dword v165, v[38:39]
	v_lshl_add_u64 v[38:39], v[14:15], 0, s[22:23]
	flat_load_dword v166, v[38:39]
	v_lshl_add_u64 v[38:39], v[12:13], 0, s[22:23]
	flat_load_dword v167, v[38:39]
	v_lshl_add_u64 v[38:39], v[10:11], 0, s[22:23]
	flat_load_dword v168, v[38:39]
	v_lshl_add_u64 v[38:39], v[8:9], 0, s[22:23]
	flat_load_dword v169, v[38:39]
	s_add_u32 s22, s22, 0x1000
	s_addc_u32 s23, s23, 0
	v_lshl_add_u64 v[38:39], v[22:23], 0, s[22:23]
	flat_load_dword v170, v[38:39]
	v_lshl_add_u64 v[38:39], v[20:21], 0, s[22:23]
	flat_load_dword v171, v[38:39]
	v_lshl_add_u64 v[38:39], v[18:19], 0, s[22:23]
	flat_load_dword v172, v[38:39]
	v_lshl_add_u64 v[38:39], v[16:17], 0, s[22:23]
	flat_load_dword v173, v[38:39]
	v_lshl_add_u64 v[38:39], v[14:15], 0, s[22:23]
	flat_load_dword v174, v[38:39]
	v_lshl_add_u64 v[38:39], v[12:13], 0, s[22:23]
	flat_load_dword v175, v[38:39]
	v_lshl_add_u64 v[38:39], v[10:11], 0, s[22:23]
	flat_load_dword v176, v[38:39]
	v_lshl_add_u64 v[38:39], v[8:9], 0, s[22:23]
	flat_load_dword v177, v[38:39]
	s_add_u32 s22, s22, 0x1000
	s_addc_u32 s23, s23, 0
	s_waitcnt vmcnt(0) lgkmcnt(0)
	ds_write_b32 v2, v146
	ds_write_b32 v2, v147 offset:264
	ds_write_b32 v2, v148 offset:528
	ds_write_b32 v2, v149 offset:792
	ds_write_b32 v2, v150 offset:1056
	ds_write_b32 v2, v151 offset:1320
	ds_write_b32 v2, v152 offset:1584
	ds_write_b32 v2, v153 offset:1848
	ds_write_b32 v2, v154 offset:2112
	ds_write_b32 v2, v155 offset:2376
	ds_write_b32 v2, v156 offset:2640
	ds_write_b32 v2, v157 offset:2904
	ds_write_b32 v2, v158 offset:3168
	ds_write_b32 v2, v159 offset:3432
	ds_write_b32 v2, v160 offset:3696
	ds_write_b32 v2, v161 offset:3960
	ds_write_b32 v2, v162 offset:4224
	ds_write_b32 v2, v163 offset:4488
	ds_write_b32 v2, v164 offset:4752
	ds_write_b32 v2, v165 offset:5016
	ds_write_b32 v2, v166 offset:5280
	ds_write_b32 v2, v167 offset:5544
	ds_write_b32 v2, v168 offset:5808
	ds_write_b32 v2, v169 offset:6072
	ds_write_b32 v2, v170 offset:6336
	ds_write_b32 v2, v171 offset:6600
	ds_write_b32 v2, v172 offset:6864
	ds_write_b32 v2, v173 offset:7128
	ds_write_b32 v2, v174 offset:7392
	ds_write_b32 v2, v175 offset:7656
	ds_write_b32 v2, v176 offset:7920
	ds_write_b32 v2, v177 offset:8184
	v_add_u32_e32 v2, 0x2100, v2
	s_cmpk_lg_i32 s22, 0x4000
	s_waitcnt lgkmcnt(0)
	ds_read_b32 v2, v25
	ds_read_b32 v7, v25 offset:132
	ds_read_b32 v9, v25 offset:264
	ds_read_b32 v10, v25 offset:396
	ds_read_b32 v11, v25 offset:528
	ds_read_b32 v14, v25 offset:660
	ds_read_b32 v15, v25 offset:792
	ds_read_b32 v16, v25 offset:924
	s_add_i32 s18, s26, 0xfffffe00
	s_lshl_b32 s22, s26, 5
	s_lshr_b32 s18, s18, 1
	s_and_b32 s25, s22, 32
	s_lshl_b64 s[22:23], s[18:19], 13
	s_waitcnt lgkmcnt(6)
	v_cvt_pk_bf16_f32 v8, v2, v7
	v_or_b32_e32 v2, s25, v24
	v_lshl_add_u64 v[12:13], v[4:5], 0, s[22:23]
	v_lshlrev_b32_e32 v2, 7, v2
	s_waitcnt lgkmcnt(4)
	v_cvt_pk_bf16_f32 v9, v9, v10
	s_waitcnt lgkmcnt(2)
	v_cvt_pk_bf16_f32 v10, v11, v14
	s_waitcnt lgkmcnt(0)
	v_cvt_pk_bf16_f32 v11, v15, v16
	v_lshl_add_u64 v[14:15], v[12:13], 0, v[2:3]
	flat_store_dwordx4 v[14:15], v[8:11]
	ds_read_b32 v2, v25 offset:32
	ds_read_b32 v7, v25 offset:164
	ds_read_b32 v9, v25 offset:296
	ds_read_b32 v10, v25 offset:428
	ds_read_b32 v11, v25 offset:560
	ds_read_b32 v14, v25 offset:692
	ds_read_b32 v15, v25 offset:824
	ds_read_b32 v16, v25 offset:956
	s_waitcnt lgkmcnt(0)
	v_cvt_pk_bf16_f32 v8, v2, v7
	v_or_b32_e32 v2, s25, v26
	v_lshlrev_b32_e32 v2, 7, v2
	v_cvt_pk_bf16_f32 v9, v9, v10
	v_cvt_pk_bf16_f32 v10, v11, v14
	v_cvt_pk_bf16_f32 v11, v15, v16
	v_lshl_add_u64 v[14:15], v[12:13], 0, v[2:3]
	flat_store_dwordx4 v[14:15], v[8:11]
	ds_read_b32 v2, v25 offset:64
	ds_read_b32 v7, v25 offset:196
	ds_read_b32 v9, v25 offset:328
	ds_read_b32 v10, v25 offset:460
	ds_read_b32 v11, v25 offset:592
	ds_read_b32 v14, v25 offset:724
	ds_read_b32 v15, v25 offset:856
	ds_read_b32 v16, v25 offset:988
	s_waitcnt lgkmcnt(0)
	v_cvt_pk_bf16_f32 v8, v2, v7
	v_or_b32_e32 v2, s25, v27
	v_lshlrev_b32_e32 v2, 7, v2
	v_cvt_pk_bf16_f32 v9, v9, v10
	v_cvt_pk_bf16_f32 v10, v11, v14
	v_cvt_pk_bf16_f32 v11, v15, v16
	v_lshl_add_u64 v[14:15], v[12:13], 0, v[2:3]
	flat_store_dwordx4 v[14:15], v[8:11]
	ds_read_b32 v2, v25 offset:96
	ds_read_b32 v7, v25 offset:228
	ds_read_b32 v9, v25 offset:360
	ds_read_b32 v10, v25 offset:492
	ds_read_b32 v11, v25 offset:624
	ds_read_b32 v14, v25 offset:756
	ds_read_b32 v15, v25 offset:888
	ds_read_b32 v16, v25 offset:1020
	s_waitcnt lgkmcnt(0)
	v_cvt_pk_bf16_f32 v8, v2, v7
	v_or_b32_e32 v2, s25, v28
	v_lshlrev_b32_e32 v2, 7, v2
	v_cvt_pk_bf16_f32 v9, v9, v10
	v_cvt_pk_bf16_f32 v10, v11, v14
	v_cvt_pk_bf16_f32 v11, v15, v16
	v_lshl_add_u64 v[12:13], v[12:13], 0, v[2:3]
	flat_store_dwordx4 v[12:13], v[8:11]
	s_waitcnt lgkmcnt(0)
	s_mov_b64 s[22:23], 0

; #define LAS __attribute__((address_space(3)))
; #define LDS_WAIT() asm volatile("s_waitcnt lgkmcnt(0)" ::: "memory")
; __device__ __forceinline__ unsigned pk2(float lo, float hi) { pk2_f2_t v = {lo, hi}; pk2_b2_t b = __builtin_convertvector(v, pk2_b2_t); return __builtin_bit_cast(unsigned, b); }
; __device__ __forceinline__ void tr_item(const float* W, int K, int N, int srccol, bf16* WT, int destrow0, int k0, LAS float* scr, int lane) {
; #pragma unroll 8
;     for (int i = 0; i < 32; ++i) { const int kk = 2 * i + (lane >> 5); scr[kk * 33 + (lane & 31)] = srccol >= 0 ? W[(size_t)(k0 + kk) * N + srccol] : 0.f; }
;     LDS_WAIT(); asm volatile("" ::: "memory");
;     const int c = lane & 7;
; #pragma unroll
;     for (int j = 0; j < 4; ++j) { const int n = (lane >> 3) + 8 * j; const LAS float* s = scr + (8 * c) * 33 + n;
;         v4u o; o.x = pk2(s[0 * 33], s[1 * 33]); o.y = pk2(s[2 * 33], s[3 * 33]); o.z = pk2(s[4 * 33], s[5 * 33]); o.w = pk2(s[6 * 33], s[7 * 33]);
;         *(v4u*)(WT + (size_t)(destrow0 + n) * K + k0 + 8 * c) = o; }
;     LDS_WAIT(); asm volatile("" ::: "memory");
; }
; __device__ __forceinline__ void p0_cmpw(const float* w1, const float* w2, const float* pos, unsigned char* ws, LAS unsigned char* lds, int gw, int NGW, int bid, int G, int wave, int lane) {
;     ...
;     for (int it = gw; it < DEPTH * 2 * 64 + DEPTH * 2 * 2; it += NGW) {
;         if (it < DEPTH * 2 * 64) { const int lk = it >> 6, r = it & 63, kb = r >> 1, nb = r & 1;
;             tr_item(w1 + (size_t)lk * 2048 * 64, 2048, 64, nb * 32 + (lane & 31), (bf16*)(ws + WS_W1T) + (size_t)lk * 64 * 2048, nb * 32, kb * 64, scr, lane); }
.LBB0_181:
	v_lshl_add_u64 v[38:39], v[22:23], 0, s[24:25]
	flat_load_dword v146, v[38:39]
	v_lshl_add_u64 v[38:39], v[20:21], 0, s[24:25]
	flat_load_dword v147, v[38:39]
	v_lshl_add_u64 v[38:39], v[18:19], 0, s[24:25]
	flat_load_dword v148, v[38:39]
	v_lshl_add_u64 v[38:39], v[16:17], 0, s[24:25]
	flat_load_dword v149, v[38:39]
	v_lshl_add_u64 v[38:39], v[14:15], 0, s[24:25]
	flat_load_dword v150, v[38:39]
	v_lshl_add_u64 v[38:39], v[12:13], 0, s[24:25]
	flat_load_dword v151, v[38:39]
	v_lshl_add_u64 v[38:39], v[10:11], 0, s[24:25]
	flat_load_dword v152, v[38:39]
	v_lshl_add_u64 v[38:39], v[8:9], 0, s[24:25]
	flat_load_dword v153, v[38:39]
	s_add_u32 s24, s24, 0x1000
	s_addc_u32 s25, s25, 0
	v_lshl_add_u64 v[38:39], v[22:23], 0, s[24:25]
	flat_load_dword v154, v[38:39]
	v_lshl_add_u64 v[38:39], v[20:21], 0, s[24:25]
	flat_load_dword v155, v[38:39]
	v_lshl_add_u64 v[38:39], v[18:19], 0, s[24:25]
	flat_load_dword v156, v[38:39]
	v_lshl_add_u64 v[38:39], v[16:17], 0, s[24:25]
	flat_load_dword v157, v[38:39]
	v_lshl_add_u64 v[38:39], v[14:15], 0, s[24:25]
	flat_load_dword v158, v[38:39]
	v_lshl_add_u64 v[38:39], v[12:13], 0, s[24:25]
	flat_load_dword v159, v[38:39]
	v_lshl_add_u64 v[38:39], v[10:11], 0, s[24:25]
	flat_load_dword v160, v[38:39]
	v_lshl_add_u64 v[38:39], v[8:9], 0, s[24:25]
	flat_load_dword v161, v[38:39]
	s_add_u32 s24, s24, 0x1000
	s_addc_u32 s25, s25, 0
	v_lshl_add_u64 v[38:39], v[22:23], 0, s[24:25]
	flat_load_dword v162, v[38:39]
	v_lshl_add_u64 v[38:39], v[20:21], 0, s[24:25]
	flat_load_dword v163, v[38:39]
	v_lshl_add_u64 v[38:39], v[18:19], 0, s[24:25]
	flat_load_dword v164, v[38:39]
	v_lshl_add_u64 v[38:39], v[16:17], 0, s[24:25]
	flat_load_dword v165, v[38:39]
	v_lshl_add_u64 v[38:39], v[14:15], 0, s[24:25]
	flat_load_dword v166, v[38:39]
	v_lshl_add_u64 v[38:39], v[12:13], 0, s[24:25]
	flat_load_dword v167, v[38:39]
	v_lshl_add_u64 v[38:39], v[10:11], 0, s[24:25]
	flat_load_dword v168, v[38:39]
	v_lshl_add_u64 v[38:39], v[8:9], 0, s[24:25]
	flat_load_dword v169, v[38:39]
	s_add_u32 s24, s24, 0x1000
	s_addc_u32 s25, s25, 0
	v_lshl_add_u64 v[38:39], v[22:23], 0, s[24:25]
	flat_load_dword v170, v[38:39]
	v_lshl_add_u64 v[38:39], v[20:21], 0, s[24:25]
	flat_load_dword v171, v[38:39]
	v_lshl_add_u64 v[38:39], v[18:19], 0, s[24:25]
	flat_load_dword v172, v[38:39]
	v_lshl_add_u64 v[38:39], v[16:17], 0, s[24:25]
	flat_load_dword v173, v[38:39]
	v_lshl_add_u64 v[38:39], v[14:15], 0, s[24:25]
	flat_load_dword v174, v[38:39]
	v_lshl_add_u64 v[38:39], v[12:13], 0, s[24:25]
	flat_load_dword v175, v[38:39]
	v_lshl_add_u64 v[38:39], v[10:11], 0, s[24:25]
	flat_load_dword v176, v[38:39]
	v_lshl_add_u64 v[38:39], v[8:9], 0, s[24:25]
	flat_load_dword v177, v[38:39]
	s_add_u32 s24, s24, 0x1000
	s_addc_u32 s25, s25, 0
	s_waitcnt vmcnt(0) lgkmcnt(0)
	ds_write_b32 v2, v146
	ds_write_b32 v2, v147 offset:264
	ds_write_b32 v2, v148 offset:528
	ds_write_b32 v2, v149 offset:792
	ds_write_b32 v2, v150 offset:1056
	ds_write_b32 v2, v151 offset:1320
	ds_write_b32 v2, v152 offset:1584
	ds_write_b32 v2, v153 offset:1848
	ds_write_b32 v2, v154 offset:2112
	ds_write_b32 v2, v155 offset:2376
	ds_write_b32 v2, v156 offset:2640
	ds_write_b32 v2, v157 offset:2904
	ds_write_b32 v2, v158 offset:3168
	ds_write_b32 v2, v159 offset:3432
	ds_write_b32 v2, v160 offset:3696
	ds_write_b32 v2, v161 offset:3960
	ds_write_b32 v2, v162 offset:4224
	ds_write_b32 v2, v163 offset:4488
	ds_write_b32 v2, v164 offset:4752
	ds_write_b32 v2, v165 offset:5016
	ds_write_b32 v2, v166 offset:5280
	ds_write_b32 v2, v167 offset:5544
	ds_write_b32 v2, v168 offset:5808
	ds_write_b32 v2, v169 offset:6072
	ds_write_b32 v2, v170 offset:6336
	ds_write_b32 v2, v171 offset:6600
	ds_write_b32 v2, v172 offset:6864
	ds_write_b32 v2, v173 offset:7128
	ds_write_b32 v2, v174 offset:7392
	ds_write_b32 v2, v175 offset:7656
	ds_write_b32 v2, v176 offset:7920
	ds_write_b32 v2, v177 offset:8184
	v_add_u32_e32 v2, 0x2100, v2
	s_cmpk_lg_i32 s24, 0x4000
	s_lshl_b32 s18, s26, 5
	s_and_b32 s18, s18, 32
	s_lshl_b64 s[22:23], s[22:23], 18
	s_waitcnt lgkmcnt(0)
	s_add_u32 s22, s21, s22
	s_addc_u32 s23, s28, s23
	s_lshl_b32 s24, s26, 6
	ds_read_b32 v2, v25
	ds_read_b32 v8, v25 offset:132
	ds_read_b32 v9, v25 offset:264
	ds_read_b32 v10, v25 offset:396
	ds_read_b32 v11, v25 offset:528
	ds_read_b32 v14, v25 offset:660
	ds_read_b32 v15, v25 offset:792
	ds_read_b32 v16, v25 offset:924
	s_and_b32 s24, s24, 0xf80
	s_add_u32 s22, s22, s24
	s_addc_u32 s23, s23, 0
	v_mov_b32_e32 v7, v3
	s_waitcnt lgkmcnt(6)
	v_cvt_pk_bf16_f32 v8, v2, v8
	v_or_b32_e32 v2, s18, v24
	v_lshl_add_u64 v[12:13], s[22:23], 0, v[6:7]
	v_lshlrev_b32_e32 v2, 12, v2
	s_waitcnt lgkmcnt(4)
	v_cvt_pk_bf16_f32 v9, v9, v10
	s_waitcnt lgkmcnt(2)
	v_cvt_pk_bf16_f32 v10, v11, v14
	s_waitcnt lgkmcnt(0)
	v_cvt_pk_bf16_f32 v11, v15, v16
	v_lshl_add_u64 v[14:15], v[12:13], 0, v[2:3]
	flat_store_dwordx4 v[14:15], v[8:11]
	ds_read_b32 v2, v25 offset:32
	ds_read_b32 v7, v25 offset:164
	ds_read_b32 v9, v25 offset:296
	ds_read_b32 v10, v25 offset:428
	ds_read_b32 v11, v25 offset:560
	ds_read_b32 v14, v25 offset:692
	ds_read_b32 v15, v25 offset:824
	ds_read_b32 v16, v25 offset:956
	s_waitcnt lgkmcnt(0)
	v_cvt_pk_bf16_f32 v8, v2, v7
	v_or_b32_e32 v2, s18, v26
	v_lshlrev_b32_e32 v2, 12, v2
	v_cvt_pk_bf16_f32 v9, v9, v10
	v_cvt_pk_bf16_f32 v10, v11, v14
	v_cvt_pk_bf16_f32 v11, v15, v16
	v_lshl_add_u64 v[14:15], v[12:13], 0, v[2:3]
	flat_store_dwordx4 v[14:15], v[8:11]
	ds_read_b32 v2, v25 offset:64
	ds_read_b32 v7, v25 offset:196
	ds_read_b32 v9, v25 offset:328
	ds_read_b32 v10, v25 offset:460
	ds_read_b32 v11, v25 offset:592
	ds_read_b32 v14, v25 offset:724
	ds_read_b32 v15, v25 offset:856
	ds_read_b32 v16, v25 offset:988
	s_waitcnt lgkmcnt(0)
	v_cvt_pk_bf16_f32 v8, v2, v7
	v_or_b32_e32 v2, s18, v27
	v_lshlrev_b32_e32 v2, 12, v2
	v_cvt_pk_bf16_f32 v9, v9, v10
	v_cvt_pk_bf16_f32 v10, v11, v14
	v_cvt_pk_bf16_f32 v11, v15, v16
	v_lshl_add_u64 v[14:15], v[12:13], 0, v[2:3]
	flat_store_dwordx4 v[14:15], v[8:11]
	ds_read_b32 v2, v25 offset:96
	ds_read_b32 v7, v25 offset:228
	ds_read_b32 v9, v25 offset:360
	ds_read_b32 v10, v25 offset:492
	ds_read_b32 v11, v25 offset:624
	ds_read_b32 v14, v25 offset:756
	ds_read_b32 v15, v25 offset:888
	ds_read_b32 v16, v25 offset:1020
	s_waitcnt lgkmcnt(0)
	v_cvt_pk_bf16_f32 v8, v2, v7
	v_or_b32_e32 v2, s18, v28
	v_lshlrev_b32_e32 v2, 12, v2
	v_cvt_pk_bf16_f32 v9, v9, v10
	v_cvt_pk_bf16_f32 v10, v11, v14
	v_cvt_pk_bf16_f32 v11, v15, v16
	v_lshl_add_u64 v[12:13], v[12:13], 0, v[2:3]
	flat_store_dwordx4 v[12:13], v[8:11]
	s_waitcnt lgkmcnt(0)
	s_branch .LBB0_174

; __device__ __forceinline__ void p0_cmpw(const float* w1, const float* w2, const float* pos, unsigned char* ws, LAS unsigned char* lds, int gw, int NGW, int bid, int G, int wave, int lane) {
;     ...
;     for (int it = bid; it < DEPTH * 2; it += G) {
;         const float* W = w1 + (size_t)it * 2048 * 64 + lane; const float* P = pos + (size_t)it * 2048; float a = 0.f;
; #pragma unroll 8
;         for (int k = wave * 256; k < wave * 256 + 256; ++k) a = fmaf(P[k], W[(size_t)k * 64], a);
;         red[wave * 64 + lane] = a;
;         __syncthreads();
;         if (wave == 0) { float s = 0.f;
; #pragma unroll
;             for (int w = 0; w < 8; ++w) s += red[w * 64 + lane];
;             ((float*)(ws + WS_PW1))[it * 64 + lane] = s; }
.LBB0_187:
	s_add_u32 s24, s22, s20
	s_addc_u32 s25, s23, s21
	v_mov_b64_e32 v[18:19], s[24:25]
	flat_load_dwordx4 v[178:181], v[18:19]
	flat_load_dwordx4 v[182:185], v[18:19] offset:16
	flat_load_dwordx4 v[214:217], v[18:19] offset:32
	flat_load_dwordx4 v[218:221], v[18:19] offset:48
	flat_load_dwordx4 v[222:225], v[18:19] offset:64
	flat_load_dwordx4 v[226:229], v[18:19] offset:80
	flat_load_dwordx4 v[230:233], v[18:19] offset:96
	flat_load_dwordx4 v[234:237], v[18:19] offset:112
	flat_load_dword v146, v[4:5]
	flat_load_dword v147, v[4:5] offset:256
	flat_load_dword v148, v[4:5] offset:512
	flat_load_dword v149, v[4:5] offset:768
	flat_load_dword v150, v[4:5] offset:1024
	flat_load_dword v151, v[4:5] offset:1280
	flat_load_dword v152, v[4:5] offset:1536
	flat_load_dword v153, v[4:5] offset:1792
	v_lshl_add_u64 v[4:5], v[4:5], 0, s[18:19]
	flat_load_dword v154, v[4:5]
	flat_load_dword v155, v[4:5] offset:256
	flat_load_dword v156, v[4:5] offset:512
	flat_load_dword v157, v[4:5] offset:768
	flat_load_dword v158, v[4:5] offset:1024
	flat_load_dword v159, v[4:5] offset:1280
	flat_load_dword v160, v[4:5] offset:1536
	flat_load_dword v161, v[4:5] offset:1792
	v_lshl_add_u64 v[4:5], v[4:5], 0, s[18:19]
	flat_load_dword v162, v[4:5]
	flat_load_dword v163, v[4:5] offset:256
	flat_load_dword v164, v[4:5] offset:512
	flat_load_dword v165, v[4:5] offset:768
	flat_load_dword v166, v[4:5] offset:1024
	flat_load_dword v167, v[4:5] offset:1280
	flat_load_dword v168, v[4:5] offset:1536
	flat_load_dword v169, v[4:5] offset:1792
	v_lshl_add_u64 v[4:5], v[4:5], 0, s[18:19]
	flat_load_dword v170, v[4:5]
	flat_load_dword v171, v[4:5] offset:256
	flat_load_dword v172, v[4:5] offset:512
	flat_load_dword v173, v[4:5] offset:768
	flat_load_dword v174, v[4:5] offset:1024
	flat_load_dword v175, v[4:5] offset:1280
	flat_load_dword v176, v[4:5] offset:1536
	flat_load_dword v177, v[4:5] offset:1792
	v_lshl_add_u64 v[4:5], v[4:5], 0, s[18:19]
	s_add_u32 s20, s20, 0x80
	s_addc_u32 s21, s21, 0
	s_cmpk_eq_i32 s20, 0x400
	s_waitcnt vmcnt(0) lgkmcnt(0)
	v_fmac_f32_e32 v8, v178, v146
	v_fmac_f32_e32 v8, v179, v147
	v_fmac_f32_e32 v8, v180, v148
	v_fmac_f32_e32 v8, v181, v149
	v_fmac_f32_e32 v8, v182, v150
	v_fmac_f32_e32 v8, v183, v151
	v_fmac_f32_e32 v8, v184, v152
	v_fmac_f32_e32 v8, v185, v153
	v_fmac_f32_e32 v8, v214, v154
	v_fmac_f32_e32 v8, v215, v155
	v_fmac_f32_e32 v8, v216, v156
	v_fmac_f32_e32 v8, v217, v157
	v_fmac_f32_e32 v8, v218, v158
	v_fmac_f32_e32 v8, v219, v159
	v_fmac_f32_e32 v8, v220, v160
	v_fmac_f32_e32 v8, v221, v161
	v_fmac_f32_e32 v8, v222, v162
	v_fmac_f32_e32 v8, v223, v163
	v_fmac_f32_e32 v8, v224, v164
	v_fmac_f32_e32 v8, v225, v165
	v_fmac_f32_e32 v8, v226, v166
	v_fmac_f32_e32 v8, v227, v167
	v_fmac_f32_e32 v8, v228, v168
	v_fmac_f32_e32 v8, v229, v169
	v_fmac_f32_e32 v8, v230, v170
	v_fmac_f32_e32 v8, v231, v171
	v_fmac_f32_e32 v8, v232, v172
	v_fmac_f32_e32 v8, v233, v173
	v_fmac_f32_e32 v8, v234, v174
	v_fmac_f32_e32 v8, v235, v175
	v_fmac_f32_e32 v8, v236, v176
	v_fmac_f32_e32 v8, v237, v177
	s_cbranch_scc0 .LBB0_187
	s_and_b64 vcc, exec, s[4:5]
	ds_write_b32 v7, v8 offset:12288
	s_waitcnt lgkmcnt(0)
	s_barrier
	s_cbranch_vccnz .LBB0_185
	ds_read2st64_b32 v[4:5], v6 offset0:48 offset1:49
	ds_read2st64_b32 v[8:9], v6 offset0:50 offset1:51
	ds_read2st64_b32 v[10:11], v6 offset0:52 offset1:53
	ds_read2st64_b32 v[12:13], v6 offset0:54 offset1:55
	v_lshl_or_b32 v14, s12, 6, v1
	s_waitcnt lgkmcnt(3)
	v_add_f32_e32 v4, 0, v4
	v_add_f32_e32 v4, v4, v5
	s_waitcnt lgkmcnt(2)
	v_add_f32_e32 v4, v4, v8
	v_add_f32_e32 v4, v4, v9
	s_waitcnt lgkmcnt(1)
	v_add_f32_e32 v4, v4, v10
	v_add_f32_e32 v4, v4, v11
	s_waitcnt lgkmcnt(0)
	v_add_f32_e32 v4, v4, v12
	v_ashrrev_i32_e32 v15, 31, v14
	v_add_f32_e32 v8, v4, v13
	v_lshl_add_u64 v[4:5], v[14:15], 2, s[14:15]
	flat_store_dword v[4:5], v8
	s_branch .LBB0_185

; __device__ __forceinline__ float log_sigmoid(float x) { return fminf(x, 0.f) - log1pf(__expf(-fabsf(x))); }
; __device__ __forceinline__ void fox_cum_block(const bf16* PROJ, const float* fbias, float* CUM, int ci, LAS unsigned char* lds, int wave, int lane) {
;     ...
;     const bf16* fp = PROJ + ((size_t)b * SEQ + 512 * wave + lane) * NINP + C_FOXF + h; float* cp = CUM + (size_t)(b * 7 + h) * SEQ + 512 * wave + lane;
;     float x[8], vals[8]; float carry = 0.f;
; #pragma unroll
;     for (int u = 0; u < 8; ++u) x[u] = bf2f(fp[(size_t)(64 * u) * NINP]);
; #pragma unroll
;     for (int u = 0; u < 8; ++u) { float v = log_sigmoid(x[u] + bias);
.LBB0_439:
	s_mul_hi_i32 s2, s14, 0x92492493
	s_add_i32 s2, s2, s14
	s_lshr_b32 s3, s2, 31
	s_ashr_i32 s2, s2, 2
	s_add_i32 s2, s2, s3
	s_mul_i32 s3, s2, 7
	s_sub_i32 s10, s14, s3
	s_ashr_i32 s11, s10, 31
	s_lshl_b64 s[12:13], s[10:11], 2
	s_add_u32 s12, s7, s12
	s_addc_u32 s13, s8, s13
	s_ashr_i32 s3, s2, 31
	v_mov_b64_e32 v[14:15], s[12:13]
	s_lshl_b64 s[2:3], s[2:3], 12
	flat_load_dword v2, v[14:15]
	v_lshl_add_u64 v[14:15], v[4:5], 0, s[2:3]
	v_mov_b64_e32 v[16:17], s[52:53]
	v_mad_u64_u32 v[16:17], s[2:3], v14, s83, v[16:17]
	v_mov_b32_e32 v14, v17
	v_mad_u64_u32 v[14:15], s[2:3], v15, s83, v[14:15]
	v_mov_b32_e32 v17, v14
	v_lshl_add_u64 v[22:23], s[10:11], 1, v[16:17]
	s_mov_b32 s3, 0
	s_mov_b32 s2, s35
	v_lshl_add_u64 v[146:147], v[22:23], 0, s[2:3]
	s_mov_b32 s2, 0xc2000
	v_lshl_add_u64 v[148:149], v[22:23], 0, s[2:3]
	s_mov_b32 s2, 0x182000
	v_lshl_add_u64 v[150:151], v[22:23], 0, s[2:3]
	s_mov_b32 s2, 0x242000
	v_lshl_add_u64 v[152:153], v[22:23], 0, s[2:3]
	s_mov_b32 s2, 0x302000
	v_lshl_add_u64 v[154:155], v[22:23], 0, s[2:3]
	s_mov_b32 s2, 0x3c2000
	v_lshl_add_u64 v[156:157], v[22:23], 0, s[2:3]
	s_mov_b32 s2, 0x482000
	v_lshl_add_u64 v[158:159], v[22:23], 0, s[2:3]
	s_mov_b32 s2, 0x542000
	v_lshl_add_u64 v[160:161], v[22:23], 0, s[2:3]
	flat_load_ushort v16, v[146:147] offset:3584
	flat_load_ushort v18, v[148:149] offset:3584
	flat_load_ushort v20, v[150:151] offset:3584
	flat_load_ushort v21, v[152:153] offset:3584
	flat_load_ushort v19, v[154:155] offset:3584
	flat_load_ushort v17, v[156:157] offset:3584
	flat_load_ushort v15, v[158:159] offset:3584
	flat_load_ushort v14, v[160:161] offset:3584
	s_mov_b32 s3, 0xbfb8aa3b
	s_mov_b32 s4, 0x3f2aaaab
	s_mov_b32 s10, 0x3f317218
	v_mov_b32_e32 v34, 0x3ecc95a3
	s_mov_b32 s11, 0x7f800000
	v_mov_b32_e32 v35, 0x7fc00000
	s_mov_b32 s12, 0x33800000
	s_waitcnt vmcnt(0) lgkmcnt(0)
	v_lshlrev_b32_e32 v16, 16, v16
	v_lshlrev_b32_e32 v18, 16, v18
	v_lshlrev_b32_e32 v20, 16, v20
	v_lshlrev_b32_e32 v21, 16, v21
	v_lshlrev_b32_e32 v19, 16, v19
	v_lshlrev_b32_e32 v17, 16, v17
	v_lshlrev_b32_e32 v15, 16, v15
	v_add_f32_e32 v18, v2, v18
	v_add_f32_e32 v20, v2, v20
	v_add_f32_e32 v21, v2, v21
	v_add_f32_e32 v19, v2, v19
	v_add_f32_e32 v17, v2, v17
	v_add_f32_e32 v22, v2, v16
	v_min_f32_e32 v16, 0, v22
	v_mul_f32_e64 v22, |v22|, s3
	v_exp_f32_e32 v22, v22
	v_add_f32_e32 v15, v2, v15
	v_add_f32_e32 v23, 1.0, v22
	v_add_f32_e32 v24, -1.0, v23
	v_sub_f32_e32 v25, v24, v23
	v_add_f32_e32 v25, 1.0, v25
	v_sub_f32_e32 v24, v22, v24
	v_add_f32_e32 v26, v24, v25
	v_frexp_mant_f32_e32 v24, v23
	v_cmp_gt_f32_e32 vcc, s4, v24
	v_cvt_f64_f32_e32 v[24:25], v23
	v_frexp_exp_i32_f64_e32 v24, v[24:25]
	v_subbrev_co_u32_e32 v24, vcc, 0, v24, vcc
	v_sub_u32_e32 v25, 0, v24
	v_ldexp_f32 v23, v23, v25
	v_ldexp_f32 v25, v26, v25
	v_add_f32_e32 v26, -1.0, v23
	v_add_f32_e32 v27, 1.0, v26
	v_sub_f32_e32 v27, v23, v27
	v_add_f32_e32 v27, v25, v27
	v_add_f32_e32 v28, v26, v27
	v_sub_f32_e32 v26, v28, v26
	v_sub_f32_e32 v26, v27, v26
	v_add_f32_e32 v27, 1.0, v23
	v_add_f32_e32 v29, -1.0, v27
	v_sub_f32_e32 v23, v23, v29
	v_add_f32_e32 v23, v25, v23
	v_add_f32_e32 v25, v27, v23
	v_sub_f32_e32 v27, v25, v27
	v_sub_f32_e32 v23, v23, v27
	v_rcp_f32_e32 v27, v25
	v_cvt_f32_i32_e32 v24, v24
	v_cmp_neq_f32_e32 vcc, s11, v22
	v_mul_f32_e32 v29, v28, v27
	v_mul_f32_e32 v30, v25, v29
	v_fma_f32 v31, v29, v25, -v30
	v_fmac_f32_e32 v31, v29, v23
	v_add_f32_e32 v32, v30, v31
	v_sub_f32_e32 v33, v28, v32
	v_sub_f32_e32 v28, v28, v33
	v_sub_f32_e32 v30, v32, v30
	v_sub_f32_e32 v28, v28, v32
	v_add_f32_e32 v26, v26, v28
	v_sub_f32_e32 v28, v30, v31
	v_add_f32_e32 v26, v28, v26
	v_add_f32_e32 v28, v33, v26
	v_mul_f32_e32 v30, v27, v28
	v_mul_f32_e32 v31, v25, v30
	v_fma_f32 v25, v30, v25, -v31
	v_fmac_f32_e32 v25, v30, v23
	v_sub_f32_e32 v23, v33, v28
	v_add_f32_e32 v23, v26, v23
	v_add_f32_e32 v26, v31, v25
	v_sub_f32_e32 v32, v28, v26
	v_sub_f32_e32 v28, v28, v32
	v_sub_f32_e32 v31, v26, v31
	v_sub_f32_e32 v26, v28, v26
	v_add_f32_e32 v23, v23, v26
	v_sub_f32_e32 v25, v31, v25
	v_add_f32_e32 v23, v25, v23
	v_add_f32_e32 v25, v29, v30
	v_add_f32_e32 v23, v32, v23
	v_sub_f32_e32 v26, v25, v29
	v_mul_f32_e32 v23, v27, v23
	v_sub_f32_e32 v26, v30, v26
	v_add_f32_e32 v23, v26, v23
	v_mul_f32_e32 v29, 0x3f317218, v24
	v_add_f32_e32 v26, v25, v23
	v_fma_f32 v30, v24, s10, -v29
	v_mul_f32_e32 v27, v26, v26
	v_fmac_f32_e32 v30, 0xb102e308, v24
	v_sub_f32_e32 v24, v26, v25
	v_fmamk_f32 v28, v27, 0x3e9b6dac, v34
	v_sub_f32_e32 v23, v23, v24
	v_add_f32_e32 v24, v29, v30
	v_fmaak_f32 v28, v27, v28, 0x3f2aaada
	v_sub_f32_e32 v25, v24, v29
	v_ldexp_f32 v29, v26, 1
	v_mul_f32_e32 v26, v26, v27
	v_mul_f32_e32 v26, v26, v28
	v_add_f32_e32 v27, v29, v26
	v_sub_f32_e32 v28, v27, v29
	v_ldexp_f32 v23, v23, 1
	v_sub_f32_e32 v26, v26, v28
	v_add_f32_e32 v23, v23, v26
	v_add_f32_e32 v26, v27, v23
	v_sub_f32_e32 v27, v26, v27
	v_sub_f32_e32 v23, v23, v27
	v_add_f32_e32 v27, v24, v26
	v_sub_f32_e32 v28, v27, v24
	v_sub_f32_e32 v29, v27, v28
	v_sub_f32_e32 v25, v30, v25
	v_sub_f32_e32 v24, v24, v29
	v_sub_f32_e32 v26, v26, v28
	v_add_f32_e32 v24, v26, v24
	v_add_f32_e32 v26, v25, v23
	v_sub_f32_e32 v28, v26, v25
	v_sub_f32_e32 v29, v26, v28
	v_sub_f32_e32 v25, v25, v29
	v_sub_f32_e32 v23, v23, v28
	v_add_f32_e32 v24, v26, v24
	v_add_f32_e32 v23, v23, v25
	v_add_f32_e32 v25, v27, v24
	v_sub_f32_e32 v26, v25, v27
	v_sub_f32_e32 v24, v24, v26
	v_add_f32_e32 v23, v23, v24
	v_add_f32_e32 v23, v25, v23
	v_cndmask_b32_e32 v23, v230, v23, vcc
	v_cmp_ngt_f32_e32 vcc, -1.0, v22
	v_min_f32_e32 v24, 0, v18
	v_mul_f32_e64 v18, |v18|, s3
	v_cndmask_b32_e32 v23, v35, v23, vcc
	v_cmp_neq_f32_e32 vcc, -1.0, v22
	v_exp_f32_e32 v18, v18
	s_waitcnt vmcnt(0) lgkmcnt(0)
; __device__ __forceinline__ float log_sigmoid(float x) { return fminf(x, 0.f) - log1pf(__expf(-fabsf(x))); }
; __device__ __forceinline__ void fox_cum_block(const bf16* PROJ, const float* fbias, float* CUM, int ci, LAS unsigned char* lds, int wave, int lane) {
;     ...
; #pragma unroll
;     for (int u = 0; u < 8; ++u) { float v = log_sigmoid(x[u] + bias);
; #pragma unroll
;         for (int o = 1; o < 64; o <<= 1) { const float y = __builtin_bit_cast(float, __builtin_amdgcn_ds_bpermute((lane - o) << 2, __builtin_bit_cast(int, v))); if (lane >= o) v += y; }
;         v += carry; vals[u] = v; carry = __builtin_bit_cast(float, __builtin_amdgcn_readlane(__builtin_bit_cast(int, v), 63)); }
	v_lshlrev_b32_e32 v14, 16, v14
	v_cndmask_b32_e32 v23, v234, v23, vcc
	v_cmp_lt_f32_e64 vcc, |v22|, s12
	v_add_f32_e32 v25, 1.0, v18
	v_add_f32_e32 v2, v2, v14
	v_cndmask_b32_e32 v22, v23, v22, vcc
	v_sub_f32_e32 v16, v16, v22
	ds_bpermute_b32 v22, v8, v16
	v_min_f32_e32 v14, 0, v2
	v_mul_f32_e64 v2, |v2|, s3
	v_exp_f32_e32 v2, v2
	s_waitcnt lgkmcnt(0)
	v_add_f32_e32 v22, v16, v22
	v_cndmask_b32_e64 v16, v22, v16, s[38:39]
	ds_bpermute_b32 v22, v9, v16
	s_waitcnt lgkmcnt(0)
	v_add_f32_e32 v22, v16, v22
	v_cndmask_b32_e64 v16, v22, v16, s[40:41]
	ds_bpermute_b32 v22, v10, v16
	s_waitcnt lgkmcnt(0)
	v_add_f32_e32 v22, v16, v22
	v_cndmask_b32_e64 v16, v22, v16, s[42:43]
	ds_bpermute_b32 v22, v11, v16
	s_waitcnt lgkmcnt(0)
	v_add_f32_e32 v22, v16, v22
	v_cndmask_b32_e64 v16, v22, v16, s[44:45]
	ds_bpermute_b32 v22, v12, v16
	s_waitcnt lgkmcnt(0)
	v_add_f32_e32 v22, v16, v22
	v_cndmask_b32_e64 v16, v22, v16, s[46:47]
	ds_bpermute_b32 v22, v13, v16
	s_waitcnt lgkmcnt(0)
	v_add_f32_e32 v22, v16, v22
	v_cndmask_b32_e64 v16, v22, v16, s[48:49]
	v_add_f32_e32 v22, -1.0, v25
	v_sub_f32_e32 v23, v22, v25
	v_add_f32_e32 v23, 1.0, v23
	v_sub_f32_e32 v22, v18, v22
	v_add_f32_e32 v26, v22, v23
	v_frexp_mant_f32_e32 v22, v25
	v_cmp_gt_f32_e32 vcc, s4, v22
	v_cvt_f64_f32_e32 v[22:23], v25
	v_frexp_exp_i32_f64_e32 v22, v[22:23]
	v_subbrev_co_u32_e32 v22, vcc, 0, v22, vcc
	v_sub_u32_e32 v23, 0, v22
	v_ldexp_f32 v25, v25, v23
	v_ldexp_f32 v23, v26, v23
	v_add_f32_e32 v26, -1.0, v25
	v_add_f32_e32 v27, 1.0, v26
	v_sub_f32_e32 v27, v25, v27
	v_add_f32_e32 v27, v23, v27
	v_add_f32_e32 v28, v26, v27
	v_sub_f32_e32 v26, v28, v26
	v_sub_f32_e32 v26, v27, v26
	v_add_f32_e32 v27, 1.0, v25
	v_add_f32_e32 v29, -1.0, v27
	v_sub_f32_e32 v25, v25, v29
	v_add_f32_e32 v23, v23, v25
	v_add_f32_e32 v25, v27, v23
	v_sub_f32_e32 v27, v25, v27
	v_sub_f32_e32 v23, v23, v27
	v_rcp_f32_e32 v27, v25
	v_cvt_f32_i32_e32 v22, v22
	v_cmp_neq_f32_e32 vcc, s11, v18
	v_add_f32_e32 v16, 0, v16
	v_mul_f32_e32 v29, v28, v27
	v_mul_f32_e32 v30, v25, v29
	v_fma_f32 v31, v29, v25, -v30
	v_fmac_f32_e32 v31, v29, v23
	v_add_f32_e32 v32, v30, v31
	v_sub_f32_e32 v33, v28, v32
	v_sub_f32_e32 v28, v28, v33
	v_sub_f32_e32 v30, v32, v30
	v_sub_f32_e32 v28, v28, v32
	v_add_f32_e32 v26, v26, v28
	v_sub_f32_e32 v28, v30, v31
	v_add_f32_e32 v26, v28, v26
	v_add_f32_e32 v28, v33, v26
	v_mul_f32_e32 v30, v27, v28
	v_mul_f32_e32 v31, v25, v30
	v_fma_f32 v25, v30, v25, -v31
	v_fmac_f32_e32 v25, v30, v23
	v_sub_f32_e32 v23, v33, v28
	v_add_f32_e32 v23, v26, v23
	v_add_f32_e32 v26, v31, v25
	v_sub_f32_e32 v32, v28, v26
	v_sub_f32_e32 v28, v28, v32
	v_sub_f32_e32 v31, v26, v31
	v_sub_f32_e32 v26, v28, v26
	v_add_f32_e32 v23, v23, v26
	v_sub_f32_e32 v25, v31, v25
	v_add_f32_e32 v23, v25, v23
	v_add_f32_e32 v25, v29, v30
	v_add_f32_e32 v23, v32, v23
	v_sub_f32_e32 v26, v25, v29
	v_mul_f32_e32 v23, v27, v23
	v_sub_f32_e32 v26, v30, v26
	v_add_f32_e32 v23, v26, v23
	v_mul_f32_e32 v29, 0x3f317218, v22
	v_add_f32_e32 v26, v25, v23
	v_fma_f32 v30, v22, s10, -v29
	v_mul_f32_e32 v27, v26, v26
	v_fmac_f32_e32 v30, 0xb102e308, v22
	v_sub_f32_e32 v22, v26, v25
	v_fmamk_f32 v28, v27, 0x3e9b6dac, v34
	v_sub_f32_e32 v22, v23, v22
	v_add_f32_e32 v23, v29, v30
	v_fmaak_f32 v28, v27, v28, 0x3f2aaada
	v_sub_f32_e32 v25, v23, v29
	v_ldexp_f32 v29, v26, 1
	v_mul_f32_e32 v26, v26, v27
	v_mul_f32_e32 v26, v26, v28
	v_add_f32_e32 v27, v29, v26
	v_sub_f32_e32 v28, v27, v29
	v_ldexp_f32 v22, v22, 1
	v_sub_f32_e32 v26, v26, v28
	v_add_f32_e32 v22, v22, v26
	v_add_f32_e32 v26, v27, v22
	v_sub_f32_e32 v27, v26, v27
	v_sub_f32_e32 v22, v22, v27
	v_add_f32_e32 v27, v23, v26
	v_sub_f32_e32 v28, v27, v23
	v_sub_f32_e32 v29, v27, v28
	v_sub_f32_e32 v25, v30, v25
	v_sub_f32_e32 v23, v23, v29
	v_sub_f32_e32 v26, v26, v28
	v_add_f32_e32 v23, v26, v23
	v_add_f32_e32 v26, v25, v22
	v_sub_f32_e32 v28, v26, v25
	v_sub_f32_e32 v29, v26, v28
	v_sub_f32_e32 v25, v25, v29
	v_sub_f32_e32 v22, v22, v28
	v_add_f32_e32 v23, v26, v23
	v_add_f32_e32 v22, v22, v25
	v_add_f32_e32 v25, v27, v23
	v_sub_f32_e32 v26, v25, v27
	v_sub_f32_e32 v23, v23, v26
	v_add_f32_e32 v22, v22, v23
	v_add_f32_e32 v22, v25, v22
	v_cndmask_b32_e32 v22, v230, v22, vcc
	v_cmp_ngt_f32_e32 vcc, -1.0, v18
	v_readlane_b32 s2, v16, 63
	s_nop 0
	v_cndmask_b32_e32 v22, v35, v22, vcc
	v_cmp_neq_f32_e32 vcc, -1.0, v18
	s_nop 1
	v_cndmask_b32_e32 v22, v234, v22, vcc
	v_cmp_lt_f32_e64 vcc, |v18|, s12
	s_nop 1
	v_cndmask_b32_e32 v18, v22, v18, vcc
	v_sub_f32_e32 v18, v24, v18
	ds_bpermute_b32 v22, v8, v18
	v_min_f32_e32 v24, 0, v20
	v_mul_f32_e64 v20, |v20|, s3
	v_exp_f32_e32 v20, v20
	s_waitcnt lgkmcnt(0)
	v_add_f32_e32 v22, v18, v22
	v_cndmask_b32_e64 v18, v22, v18, s[38:39]
	ds_bpermute_b32 v22, v9, v18
	v_add_f32_e32 v25, 1.0, v20
	s_waitcnt lgkmcnt(0)
	v_add_f32_e32 v22, v18, v22
	v_cndmask_b32_e64 v18, v22, v18, s[40:41]
	ds_bpermute_b32 v22, v10, v18
	s_waitcnt lgkmcnt(0)
	v_add_f32_e32 v22, v18, v22
	v_cndmask_b32_e64 v18, v22, v18, s[42:43]
	ds_bpermute_b32 v22, v11, v18
	s_waitcnt lgkmcnt(0)
	v_add_f32_e32 v22, v18, v22
	v_cndmask_b32_e64 v18, v22, v18, s[44:45]
	ds_bpermute_b32 v22, v12, v18
	s_waitcnt lgkmcnt(0)
	v_add_f32_e32 v22, v18, v22
	v_cndmask_b32_e64 v18, v22, v18, s[46:47]
	ds_bpermute_b32 v22, v13, v18
	s_waitcnt lgkmcnt(0)
; __device__ __forceinline__ float log_sigmoid(float x) { return fminf(x, 0.f) - log1pf(__expf(-fabsf(x))); }
; __device__ __forceinline__ void fox_cum_block(const bf16* PROJ, const float* fbias, float* CUM, int ci, LAS unsigned char* lds, int wave, int lane) {
;     ...
; #pragma unroll
;     for (int u = 0; u < 8; ++u) { float v = log_sigmoid(x[u] + bias);
; #pragma unroll
;         for (int o = 1; o < 64; o <<= 1) { const float y = __builtin_bit_cast(float, __builtin_amdgcn_ds_bpermute((lane - o) << 2, __builtin_bit_cast(int, v))); if (lane >= o) v += y; }
;         v += carry; vals[u] = v; carry = __builtin_bit_cast(float, __builtin_amdgcn_readlane(__builtin_bit_cast(int, v), 63)); }
	v_add_f32_e32 v22, v18, v22
	v_cndmask_b32_e64 v18, v22, v18, s[48:49]
	v_add_f32_e32 v22, -1.0, v25
	v_sub_f32_e32 v23, v22, v25
	v_add_f32_e32 v23, 1.0, v23
	v_sub_f32_e32 v22, v20, v22
	v_add_f32_e32 v26, v22, v23
	v_frexp_mant_f32_e32 v22, v25
	v_cmp_gt_f32_e32 vcc, s4, v22
	v_cvt_f64_f32_e32 v[22:23], v25
	v_frexp_exp_i32_f64_e32 v22, v[22:23]
	v_subbrev_co_u32_e32 v22, vcc, 0, v22, vcc
	v_sub_u32_e32 v23, 0, v22
	v_ldexp_f32 v25, v25, v23
	v_ldexp_f32 v23, v26, v23
	v_add_f32_e32 v26, -1.0, v25
	v_add_f32_e32 v27, 1.0, v26
	v_sub_f32_e32 v27, v25, v27
	v_add_f32_e32 v27, v23, v27
	v_add_f32_e32 v28, v26, v27
	v_sub_f32_e32 v26, v28, v26
	v_sub_f32_e32 v26, v27, v26
	v_add_f32_e32 v27, 1.0, v25
	v_add_f32_e32 v29, -1.0, v27
	v_sub_f32_e32 v25, v25, v29
	v_add_f32_e32 v23, v23, v25
	v_add_f32_e32 v25, v27, v23
	v_sub_f32_e32 v27, v25, v27
	v_sub_f32_e32 v23, v23, v27
	v_rcp_f32_e32 v27, v25
	v_cvt_f32_i32_e32 v22, v22
	v_cmp_neq_f32_e32 vcc, s11, v20
	v_add_f32_e32 v18, s2, v18
	v_mul_f32_e32 v29, v28, v27
	v_mul_f32_e32 v30, v25, v29
	v_fma_f32 v31, v29, v25, -v30
	v_fmac_f32_e32 v31, v29, v23
	v_add_f32_e32 v32, v30, v31
	v_sub_f32_e32 v33, v28, v32
	v_sub_f32_e32 v28, v28, v33
	v_sub_f32_e32 v30, v32, v30
	v_sub_f32_e32 v28, v28, v32
	v_add_f32_e32 v26, v26, v28
	v_sub_f32_e32 v28, v30, v31
	v_add_f32_e32 v26, v28, v26
	v_add_f32_e32 v28, v33, v26
	v_mul_f32_e32 v30, v27, v28
	v_mul_f32_e32 v31, v25, v30
	v_fma_f32 v25, v30, v25, -v31
	v_fmac_f32_e32 v25, v30, v23
	v_sub_f32_e32 v23, v33, v28
	v_add_f32_e32 v23, v26, v23
	v_add_f32_e32 v26, v31, v25
	v_sub_f32_e32 v32, v28, v26
	v_sub_f32_e32 v28, v28, v32
	v_sub_f32_e32 v31, v26, v31
	v_sub_f32_e32 v26, v28, v26
	v_add_f32_e32 v23, v23, v26
	v_sub_f32_e32 v25, v31, v25
	v_add_f32_e32 v23, v25, v23
	v_add_f32_e32 v25, v29, v30
	v_add_f32_e32 v23, v32, v23
	v_sub_f32_e32 v26, v25, v29
	v_mul_f32_e32 v23, v27, v23
	v_sub_f32_e32 v26, v30, v26
	v_add_f32_e32 v23, v26, v23
	v_mul_f32_e32 v29, 0x3f317218, v22
	v_add_f32_e32 v26, v25, v23
	v_fma_f32 v30, v22, s10, -v29
	v_mul_f32_e32 v27, v26, v26
	v_fmac_f32_e32 v30, 0xb102e308, v22
	v_sub_f32_e32 v22, v26, v25
	v_fmamk_f32 v28, v27, 0x3e9b6dac, v34
	v_sub_f32_e32 v22, v23, v22
	v_add_f32_e32 v23, v29, v30
	v_fmaak_f32 v28, v27, v28, 0x3f2aaada
	v_sub_f32_e32 v25, v23, v29
	v_ldexp_f32 v29, v26, 1
	v_mul_f32_e32 v26, v26, v27
	v_mul_f32_e32 v26, v26, v28
	v_add_f32_e32 v27, v29, v26
	v_sub_f32_e32 v28, v27, v29
	v_ldexp_f32 v22, v22, 1
	v_sub_f32_e32 v26, v26, v28
	v_add_f32_e32 v22, v22, v26
	v_add_f32_e32 v26, v27, v22
	v_sub_f32_e32 v27, v26, v27
	v_sub_f32_e32 v22, v22, v27
	v_add_f32_e32 v27, v23, v26
	v_sub_f32_e32 v28, v27, v23
	v_sub_f32_e32 v29, v27, v28
	v_sub_f32_e32 v25, v30, v25
	v_sub_f32_e32 v23, v23, v29
	v_sub_f32_e32 v26, v26, v28
	v_add_f32_e32 v23, v26, v23
	v_add_f32_e32 v26, v25, v22
	v_sub_f32_e32 v28, v26, v25
	v_sub_f32_e32 v29, v26, v28
	v_sub_f32_e32 v25, v25, v29
	v_sub_f32_e32 v22, v22, v28
	v_add_f32_e32 v23, v26, v23
	v_add_f32_e32 v22, v22, v25
	v_add_f32_e32 v25, v27, v23
	v_sub_f32_e32 v26, v25, v27
	v_sub_f32_e32 v23, v23, v26
	v_add_f32_e32 v22, v22, v23
	v_add_f32_e32 v22, v25, v22
	v_cndmask_b32_e32 v22, v230, v22, vcc
	v_cmp_ngt_f32_e32 vcc, -1.0, v20
	v_readlane_b32 s2, v18, 63
	s_nop 0
	v_cndmask_b32_e32 v22, v35, v22, vcc
	v_cmp_neq_f32_e32 vcc, -1.0, v20
	s_nop 1
	v_cndmask_b32_e32 v22, v234, v22, vcc
	v_cmp_lt_f32_e64 vcc, |v20|, s12
	s_nop 1
	v_cndmask_b32_e32 v20, v22, v20, vcc
	v_sub_f32_e32 v20, v24, v20
	ds_bpermute_b32 v22, v8, v20
	v_min_f32_e32 v24, 0, v21
	v_mul_f32_e64 v21, |v21|, s3
	v_exp_f32_e32 v21, v21
	s_waitcnt lgkmcnt(0)
	v_add_f32_e32 v22, v20, v22
	v_cndmask_b32_e64 v20, v22, v20, s[38:39]
	ds_bpermute_b32 v22, v9, v20
	v_add_f32_e32 v25, 1.0, v21
	s_waitcnt lgkmcnt(0)
	v_add_f32_e32 v22, v20, v22
	v_cndmask_b32_e64 v20, v22, v20, s[40:41]
	ds_bpermute_b32 v22, v10, v20
	s_waitcnt lgkmcnt(0)
	v_add_f32_e32 v22, v20, v22
	v_cndmask_b32_e64 v20, v22, v20, s[42:43]
	ds_bpermute_b32 v22, v11, v20
	s_waitcnt lgkmcnt(0)
	v_add_f32_e32 v22, v20, v22
	v_cndmask_b32_e64 v20, v22, v20, s[44:45]
	ds_bpermute_b32 v22, v12, v20
	s_waitcnt lgkmcnt(0)
	v_add_f32_e32 v22, v20, v22
	v_cndmask_b32_e64 v20, v22, v20, s[46:47]
	ds_bpermute_b32 v22, v13, v20
	s_waitcnt lgkmcnt(0)
; __device__ __forceinline__ float log_sigmoid(float x) { return fminf(x, 0.f) - log1pf(__expf(-fabsf(x))); }
; __device__ __forceinline__ void fox_cum_block(const bf16* PROJ, const float* fbias, float* CUM, int ci, LAS unsigned char* lds, int wave, int lane) {
;     ...
; #pragma unroll
;     for (int u = 0; u < 8; ++u) { float v = log_sigmoid(x[u] + bias);
; #pragma unroll
;         for (int o = 1; o < 64; o <<= 1) { const float y = __builtin_bit_cast(float, __builtin_amdgcn_ds_bpermute((lane - o) << 2, __builtin_bit_cast(int, v))); if (lane >= o) v += y; }
;         v += carry; vals[u] = v; carry = __builtin_bit_cast(float, __builtin_amdgcn_readlane(__builtin_bit_cast(int, v), 63)); }
	v_add_f32_e32 v22, v20, v22
	v_cndmask_b32_e64 v20, v22, v20, s[48:49]
	v_add_f32_e32 v22, -1.0, v25
	v_sub_f32_e32 v23, v22, v25
	v_add_f32_e32 v23, 1.0, v23
	v_sub_f32_e32 v22, v21, v22
	v_add_f32_e32 v26, v22, v23
	v_frexp_mant_f32_e32 v22, v25
	v_cmp_gt_f32_e32 vcc, s4, v22
	v_cvt_f64_f32_e32 v[22:23], v25
	v_frexp_exp_i32_f64_e32 v22, v[22:23]
	v_subbrev_co_u32_e32 v22, vcc, 0, v22, vcc
	v_sub_u32_e32 v23, 0, v22
	v_ldexp_f32 v25, v25, v23
	v_ldexp_f32 v23, v26, v23
	v_add_f32_e32 v26, -1.0, v25
	v_add_f32_e32 v27, 1.0, v26
	v_sub_f32_e32 v27, v25, v27
	v_add_f32_e32 v27, v23, v27
	v_add_f32_e32 v28, v26, v27
	v_sub_f32_e32 v26, v28, v26
	v_sub_f32_e32 v26, v27, v26
	v_add_f32_e32 v27, 1.0, v25
	v_add_f32_e32 v29, -1.0, v27
	v_sub_f32_e32 v25, v25, v29
	v_add_f32_e32 v23, v23, v25
	v_add_f32_e32 v25, v27, v23
	v_sub_f32_e32 v27, v25, v27
	v_sub_f32_e32 v23, v23, v27
	v_rcp_f32_e32 v27, v25
	v_cvt_f32_i32_e32 v22, v22
	v_cmp_neq_f32_e32 vcc, s11, v21
	v_add_f32_e32 v20, s2, v20
	v_mul_f32_e32 v29, v28, v27
	v_mul_f32_e32 v30, v25, v29
	v_fma_f32 v31, v29, v25, -v30
	v_fmac_f32_e32 v31, v29, v23
	v_add_f32_e32 v32, v30, v31
	v_sub_f32_e32 v33, v28, v32
	v_sub_f32_e32 v28, v28, v33
	v_sub_f32_e32 v30, v32, v30
	v_sub_f32_e32 v28, v28, v32
	v_add_f32_e32 v26, v26, v28
	v_sub_f32_e32 v28, v30, v31
	v_add_f32_e32 v26, v28, v26
	v_add_f32_e32 v28, v33, v26
	v_mul_f32_e32 v30, v27, v28
	v_mul_f32_e32 v31, v25, v30
	v_fma_f32 v25, v30, v25, -v31
	v_fmac_f32_e32 v25, v30, v23
	v_sub_f32_e32 v23, v33, v28
	v_add_f32_e32 v23, v26, v23
	v_add_f32_e32 v26, v31, v25
	v_sub_f32_e32 v32, v28, v26
	v_sub_f32_e32 v28, v28, v32
	v_sub_f32_e32 v31, v26, v31
	v_sub_f32_e32 v26, v28, v26
	v_add_f32_e32 v23, v23, v26
	v_sub_f32_e32 v25, v31, v25
	v_add_f32_e32 v23, v25, v23
	v_add_f32_e32 v25, v29, v30
	v_add_f32_e32 v23, v32, v23
	v_sub_f32_e32 v26, v25, v29
	v_mul_f32_e32 v23, v27, v23
	v_sub_f32_e32 v26, v30, v26
	v_add_f32_e32 v23, v26, v23
	v_mul_f32_e32 v29, 0x3f317218, v22
	v_add_f32_e32 v26, v25, v23
	v_fma_f32 v30, v22, s10, -v29
	v_mul_f32_e32 v27, v26, v26
	v_fmac_f32_e32 v30, 0xb102e308, v22
	v_sub_f32_e32 v22, v26, v25
	v_fmamk_f32 v28, v27, 0x3e9b6dac, v34
	v_sub_f32_e32 v22, v23, v22
	v_add_f32_e32 v23, v29, v30
	v_fmaak_f32 v28, v27, v28, 0x3f2aaada
	v_sub_f32_e32 v25, v23, v29
	v_ldexp_f32 v29, v26, 1
	v_mul_f32_e32 v26, v26, v27
	v_mul_f32_e32 v26, v26, v28
	v_add_f32_e32 v27, v29, v26
	v_sub_f32_e32 v28, v27, v29
	v_ldexp_f32 v22, v22, 1
	v_sub_f32_e32 v26, v26, v28
	v_add_f32_e32 v22, v22, v26
	v_add_f32_e32 v26, v27, v22
	v_sub_f32_e32 v27, v26, v27
	v_sub_f32_e32 v22, v22, v27
	v_add_f32_e32 v27, v23, v26
	v_sub_f32_e32 v28, v27, v23
	v_sub_f32_e32 v29, v27, v28
	v_sub_f32_e32 v25, v30, v25
	v_sub_f32_e32 v23, v23, v29
	v_sub_f32_e32 v26, v26, v28
	v_add_f32_e32 v23, v26, v23
	v_add_f32_e32 v26, v25, v22
	v_sub_f32_e32 v28, v26, v25
	v_sub_f32_e32 v29, v26, v28
	v_sub_f32_e32 v25, v25, v29
	v_sub_f32_e32 v22, v22, v28
	v_add_f32_e32 v23, v26, v23
	v_add_f32_e32 v22, v22, v25
	v_add_f32_e32 v25, v27, v23
	v_sub_f32_e32 v26, v25, v27
	v_sub_f32_e32 v23, v23, v26
	v_add_f32_e32 v22, v22, v23
	v_add_f32_e32 v22, v25, v22
	v_cndmask_b32_e32 v22, v230, v22, vcc
	v_cmp_ngt_f32_e32 vcc, -1.0, v21
	v_readlane_b32 s2, v20, 63
	s_nop 0
	v_cndmask_b32_e32 v22, v35, v22, vcc
	v_cmp_neq_f32_e32 vcc, -1.0, v21
	s_nop 1
	v_cndmask_b32_e32 v22, v234, v22, vcc
	v_cmp_lt_f32_e64 vcc, |v21|, s12
	s_nop 1
	v_cndmask_b32_e32 v21, v22, v21, vcc
	v_sub_f32_e32 v21, v24, v21
	ds_bpermute_b32 v22, v8, v21
	v_min_f32_e32 v24, 0, v19
	v_mul_f32_e64 v19, |v19|, s3
	v_exp_f32_e32 v19, v19
	s_waitcnt lgkmcnt(0)
	v_add_f32_e32 v22, v21, v22
	v_cndmask_b32_e64 v21, v22, v21, s[38:39]
	ds_bpermute_b32 v22, v9, v21
	v_add_f32_e32 v25, 1.0, v19
	s_waitcnt lgkmcnt(0)
	v_add_f32_e32 v22, v21, v22
	v_cndmask_b32_e64 v21, v22, v21, s[40:41]
	ds_bpermute_b32 v22, v10, v21
	s_waitcnt lgkmcnt(0)
	v_add_f32_e32 v22, v21, v22
	v_cndmask_b32_e64 v21, v22, v21, s[42:43]
	ds_bpermute_b32 v22, v11, v21
	s_waitcnt lgkmcnt(0)
	v_add_f32_e32 v22, v21, v22
	v_cndmask_b32_e64 v21, v22, v21, s[44:45]
	ds_bpermute_b32 v22, v12, v21
	s_waitcnt lgkmcnt(0)
	v_add_f32_e32 v22, v21, v22
	v_cndmask_b32_e64 v21, v22, v21, s[46:47]
	ds_bpermute_b32 v22, v13, v21
	s_waitcnt lgkmcnt(0)
; __device__ __forceinline__ float log_sigmoid(float x) { return fminf(x, 0.f) - log1pf(__expf(-fabsf(x))); }
; __device__ __forceinline__ void fox_cum_block(const bf16* PROJ, const float* fbias, float* CUM, int ci, LAS unsigned char* lds, int wave, int lane) {
;     ...
; #pragma unroll
;     for (int u = 0; u < 8; ++u) { float v = log_sigmoid(x[u] + bias);
; #pragma unroll
;         for (int o = 1; o < 64; o <<= 1) { const float y = __builtin_bit_cast(float, __builtin_amdgcn_ds_bpermute((lane - o) << 2, __builtin_bit_cast(int, v))); if (lane >= o) v += y; }
;         v += carry; vals[u] = v; carry = __builtin_bit_cast(float, __builtin_amdgcn_readlane(__builtin_bit_cast(int, v), 63)); }
	v_add_f32_e32 v22, v21, v22
	v_cndmask_b32_e64 v21, v22, v21, s[48:49]
	v_add_f32_e32 v22, -1.0, v25
	v_sub_f32_e32 v23, v22, v25
	v_add_f32_e32 v23, 1.0, v23
	v_sub_f32_e32 v22, v19, v22
	v_add_f32_e32 v26, v22, v23
	v_frexp_mant_f32_e32 v22, v25
	v_cmp_gt_f32_e32 vcc, s4, v22
	v_cvt_f64_f32_e32 v[22:23], v25
	v_frexp_exp_i32_f64_e32 v22, v[22:23]
	v_subbrev_co_u32_e32 v22, vcc, 0, v22, vcc
	v_sub_u32_e32 v23, 0, v22
	v_ldexp_f32 v25, v25, v23
	v_ldexp_f32 v23, v26, v23
	v_add_f32_e32 v26, -1.0, v25
	v_add_f32_e32 v27, 1.0, v26
	v_sub_f32_e32 v27, v25, v27
	v_add_f32_e32 v27, v23, v27
	v_add_f32_e32 v28, v26, v27
	v_sub_f32_e32 v26, v28, v26
	v_sub_f32_e32 v26, v27, v26
	v_add_f32_e32 v27, 1.0, v25
	v_add_f32_e32 v29, -1.0, v27
	v_sub_f32_e32 v25, v25, v29
	v_add_f32_e32 v23, v23, v25
	v_add_f32_e32 v25, v27, v23
	v_sub_f32_e32 v27, v25, v27
	v_sub_f32_e32 v23, v23, v27
	v_rcp_f32_e32 v27, v25
	v_cvt_f32_i32_e32 v22, v22
	v_cmp_neq_f32_e32 vcc, s11, v19
	v_add_f32_e32 v21, s2, v21
	v_mul_f32_e32 v29, v28, v27
	v_mul_f32_e32 v30, v25, v29
	v_fma_f32 v31, v29, v25, -v30
	v_fmac_f32_e32 v31, v29, v23
	v_add_f32_e32 v32, v30, v31
	v_sub_f32_e32 v33, v28, v32
	v_sub_f32_e32 v28, v28, v33
	v_sub_f32_e32 v30, v32, v30
	v_sub_f32_e32 v28, v28, v32
	v_add_f32_e32 v26, v26, v28
	v_sub_f32_e32 v28, v30, v31
	v_add_f32_e32 v26, v28, v26
	v_add_f32_e32 v28, v33, v26
	v_mul_f32_e32 v30, v27, v28
	v_mul_f32_e32 v31, v25, v30
	v_fma_f32 v25, v30, v25, -v31
	v_fmac_f32_e32 v25, v30, v23
	v_sub_f32_e32 v23, v33, v28
	v_add_f32_e32 v23, v26, v23
	v_add_f32_e32 v26, v31, v25
	v_sub_f32_e32 v32, v28, v26
	v_sub_f32_e32 v28, v28, v32
	v_sub_f32_e32 v31, v26, v31
	v_sub_f32_e32 v26, v28, v26
	v_add_f32_e32 v23, v23, v26
	v_sub_f32_e32 v25, v31, v25
	v_add_f32_e32 v23, v25, v23
	v_add_f32_e32 v25, v29, v30
	v_add_f32_e32 v23, v32, v23
	v_sub_f32_e32 v26, v25, v29
	v_mul_f32_e32 v23, v27, v23
	v_sub_f32_e32 v26, v30, v26
	v_add_f32_e32 v23, v26, v23
	v_mul_f32_e32 v29, 0x3f317218, v22
	v_add_f32_e32 v26, v25, v23
	v_fma_f32 v30, v22, s10, -v29
	v_mul_f32_e32 v27, v26, v26
	v_fmac_f32_e32 v30, 0xb102e308, v22
	v_sub_f32_e32 v22, v26, v25
	v_fmamk_f32 v28, v27, 0x3e9b6dac, v34
	v_sub_f32_e32 v22, v23, v22
	v_add_f32_e32 v23, v29, v30
	v_fmaak_f32 v28, v27, v28, 0x3f2aaada
	v_sub_f32_e32 v25, v23, v29
	v_ldexp_f32 v29, v26, 1
	v_mul_f32_e32 v26, v26, v27
	v_mul_f32_e32 v26, v26, v28
	v_add_f32_e32 v27, v29, v26
	v_sub_f32_e32 v28, v27, v29
	v_ldexp_f32 v22, v22, 1
	v_sub_f32_e32 v26, v26, v28
	v_add_f32_e32 v22, v22, v26
	v_add_f32_e32 v26, v27, v22
	v_sub_f32_e32 v27, v26, v27
	v_sub_f32_e32 v22, v22, v27
	v_add_f32_e32 v27, v23, v26
	v_sub_f32_e32 v28, v27, v23
	v_sub_f32_e32 v29, v27, v28
	v_sub_f32_e32 v25, v30, v25
	v_sub_f32_e32 v23, v23, v29
	v_sub_f32_e32 v26, v26, v28
	v_add_f32_e32 v23, v26, v23
	v_add_f32_e32 v26, v25, v22
	v_sub_f32_e32 v28, v26, v25
	v_sub_f32_e32 v29, v26, v28
	v_sub_f32_e32 v25, v25, v29
	v_sub_f32_e32 v22, v22, v28
	v_add_f32_e32 v23, v26, v23
	v_add_f32_e32 v22, v22, v25
	v_add_f32_e32 v25, v27, v23
	v_sub_f32_e32 v26, v25, v27
	v_sub_f32_e32 v23, v23, v26
	v_add_f32_e32 v22, v22, v23
	v_add_f32_e32 v22, v25, v22
	v_cndmask_b32_e32 v22, v230, v22, vcc
	v_cmp_ngt_f32_e32 vcc, -1.0, v19
	v_readlane_b32 s2, v21, 63
	s_nop 0
	v_cndmask_b32_e32 v22, v35, v22, vcc
	v_cmp_neq_f32_e32 vcc, -1.0, v19
	s_nop 1
	v_cndmask_b32_e32 v22, v234, v22, vcc
	v_cmp_lt_f32_e64 vcc, |v19|, s12
	s_nop 1
	v_cndmask_b32_e32 v19, v22, v19, vcc
	v_sub_f32_e32 v19, v24, v19
	ds_bpermute_b32 v22, v8, v19
	v_min_f32_e32 v24, 0, v17
	v_mul_f32_e64 v17, |v17|, s3
	v_exp_f32_e32 v17, v17
	s_waitcnt lgkmcnt(0)
	v_add_f32_e32 v22, v19, v22
	v_cndmask_b32_e64 v19, v22, v19, s[38:39]
	ds_bpermute_b32 v22, v9, v19
	v_add_f32_e32 v25, 1.0, v17
	s_waitcnt lgkmcnt(0)
	v_add_f32_e32 v22, v19, v22
	v_cndmask_b32_e64 v19, v22, v19, s[40:41]
	ds_bpermute_b32 v22, v10, v19
	s_waitcnt lgkmcnt(0)
	v_add_f32_e32 v22, v19, v22
	v_cndmask_b32_e64 v19, v22, v19, s[42:43]
	ds_bpermute_b32 v22, v11, v19
	s_waitcnt lgkmcnt(0)
	v_add_f32_e32 v22, v19, v22
	v_cndmask_b32_e64 v19, v22, v19, s[44:45]
	ds_bpermute_b32 v22, v12, v19
	s_waitcnt lgkmcnt(0)
	v_add_f32_e32 v22, v19, v22
	v_cndmask_b32_e64 v19, v22, v19, s[46:47]
	ds_bpermute_b32 v22, v13, v19
	s_waitcnt lgkmcnt(0)
; __device__ __forceinline__ float log_sigmoid(float x) { return fminf(x, 0.f) - log1pf(__expf(-fabsf(x))); }
; __device__ __forceinline__ void fox_cum_block(const bf16* PROJ, const float* fbias, float* CUM, int ci, LAS unsigned char* lds, int wave, int lane) {
;     ...
; #pragma unroll
;     for (int u = 0; u < 8; ++u) { float v = log_sigmoid(x[u] + bias);
; #pragma unroll
;         for (int o = 1; o < 64; o <<= 1) { const float y = __builtin_bit_cast(float, __builtin_amdgcn_ds_bpermute((lane - o) << 2, __builtin_bit_cast(int, v))); if (lane >= o) v += y; }
;         v += carry; vals[u] = v; carry = __builtin_bit_cast(float, __builtin_amdgcn_readlane(__builtin_bit_cast(int, v), 63)); }
	v_add_f32_e32 v22, v19, v22
	v_cndmask_b32_e64 v19, v22, v19, s[48:49]
	v_add_f32_e32 v22, -1.0, v25
	v_sub_f32_e32 v23, v22, v25
	v_add_f32_e32 v23, 1.0, v23
	v_sub_f32_e32 v22, v17, v22
	v_add_f32_e32 v26, v22, v23
	v_frexp_mant_f32_e32 v22, v25
	v_cmp_gt_f32_e32 vcc, s4, v22
	v_cvt_f64_f32_e32 v[22:23], v25
	v_frexp_exp_i32_f64_e32 v22, v[22:23]
	v_subbrev_co_u32_e32 v22, vcc, 0, v22, vcc
	v_sub_u32_e32 v23, 0, v22
	v_ldexp_f32 v25, v25, v23
	v_ldexp_f32 v23, v26, v23
	v_add_f32_e32 v26, -1.0, v25
	v_add_f32_e32 v27, 1.0, v26
	v_sub_f32_e32 v27, v25, v27
	v_add_f32_e32 v27, v23, v27
	v_add_f32_e32 v28, v26, v27
	v_sub_f32_e32 v26, v28, v26
	v_sub_f32_e32 v26, v27, v26
	v_add_f32_e32 v27, 1.0, v25
	v_add_f32_e32 v29, -1.0, v27
	v_sub_f32_e32 v25, v25, v29
	v_add_f32_e32 v23, v23, v25
	v_add_f32_e32 v25, v27, v23
	v_sub_f32_e32 v27, v25, v27
	v_sub_f32_e32 v23, v23, v27
	v_rcp_f32_e32 v27, v25
	v_cvt_f32_i32_e32 v22, v22
	v_cmp_neq_f32_e32 vcc, s11, v17
	v_add_f32_e32 v19, s2, v19
	v_mul_f32_e32 v29, v28, v27
	v_mul_f32_e32 v30, v25, v29
	v_fma_f32 v31, v29, v25, -v30
	v_fmac_f32_e32 v31, v29, v23
	v_add_f32_e32 v32, v30, v31
	v_sub_f32_e32 v33, v28, v32
	v_sub_f32_e32 v28, v28, v33
	v_sub_f32_e32 v30, v32, v30
	v_sub_f32_e32 v28, v28, v32
	v_add_f32_e32 v26, v26, v28
	v_sub_f32_e32 v28, v30, v31
	v_add_f32_e32 v26, v28, v26
	v_add_f32_e32 v28, v33, v26
	v_mul_f32_e32 v30, v27, v28
	v_mul_f32_e32 v31, v25, v30
	v_fma_f32 v25, v30, v25, -v31
	v_fmac_f32_e32 v25, v30, v23
	v_sub_f32_e32 v23, v33, v28
	v_add_f32_e32 v23, v26, v23
	v_add_f32_e32 v26, v31, v25
	v_sub_f32_e32 v32, v28, v26
	v_sub_f32_e32 v28, v28, v32
	v_sub_f32_e32 v31, v26, v31
	v_sub_f32_e32 v26, v28, v26
	v_add_f32_e32 v23, v23, v26
	v_sub_f32_e32 v25, v31, v25
	v_add_f32_e32 v23, v25, v23
	v_add_f32_e32 v25, v29, v30
	v_add_f32_e32 v23, v32, v23
	v_sub_f32_e32 v26, v25, v29
	v_mul_f32_e32 v23, v27, v23
	v_sub_f32_e32 v26, v30, v26
	v_add_f32_e32 v23, v26, v23
	v_mul_f32_e32 v29, 0x3f317218, v22
	v_add_f32_e32 v26, v25, v23
	v_fma_f32 v30, v22, s10, -v29
	v_mul_f32_e32 v27, v26, v26
	v_fmac_f32_e32 v30, 0xb102e308, v22
	v_sub_f32_e32 v22, v26, v25
	v_fmamk_f32 v28, v27, 0x3e9b6dac, v34
	v_sub_f32_e32 v22, v23, v22
	v_add_f32_e32 v23, v29, v30
	v_fmaak_f32 v28, v27, v28, 0x3f2aaada
	v_sub_f32_e32 v25, v23, v29
	v_ldexp_f32 v29, v26, 1
	v_mul_f32_e32 v26, v26, v27
	v_mul_f32_e32 v26, v26, v28
	v_add_f32_e32 v27, v29, v26
	v_sub_f32_e32 v28, v27, v29
	v_ldexp_f32 v22, v22, 1
	v_sub_f32_e32 v26, v26, v28
	v_add_f32_e32 v22, v22, v26
	v_add_f32_e32 v26, v27, v22
	v_sub_f32_e32 v27, v26, v27
	v_sub_f32_e32 v22, v22, v27
	v_add_f32_e32 v27, v23, v26
	v_sub_f32_e32 v28, v27, v23
	v_sub_f32_e32 v29, v27, v28
	v_sub_f32_e32 v25, v30, v25
	v_sub_f32_e32 v23, v23, v29
	v_sub_f32_e32 v26, v26, v28
	v_add_f32_e32 v23, v26, v23
	v_add_f32_e32 v26, v25, v22
	v_sub_f32_e32 v28, v26, v25
	v_sub_f32_e32 v29, v26, v28
	v_sub_f32_e32 v25, v25, v29
	v_sub_f32_e32 v22, v22, v28
	v_add_f32_e32 v23, v26, v23
	v_add_f32_e32 v22, v22, v25
	v_add_f32_e32 v25, v27, v23
	v_sub_f32_e32 v26, v25, v27
	v_sub_f32_e32 v23, v23, v26
	v_add_f32_e32 v22, v22, v23
	v_add_f32_e32 v22, v25, v22
	v_cndmask_b32_e32 v22, v230, v22, vcc
	v_cmp_ngt_f32_e32 vcc, -1.0, v17
	v_readlane_b32 s2, v19, 63
	s_nop 0
	v_cndmask_b32_e32 v22, v35, v22, vcc
	v_cmp_neq_f32_e32 vcc, -1.0, v17
	s_nop 1
	v_cndmask_b32_e32 v22, v234, v22, vcc
	v_cmp_lt_f32_e64 vcc, |v17|, s12
	s_nop 1
	v_cndmask_b32_e32 v17, v22, v17, vcc
	v_sub_f32_e32 v17, v24, v17
	ds_bpermute_b32 v22, v8, v17
	v_min_f32_e32 v24, 0, v15
	v_mul_f32_e64 v15, |v15|, s3
	v_exp_f32_e32 v15, v15
	s_waitcnt lgkmcnt(0)
	v_add_f32_e32 v22, v17, v22
	v_cndmask_b32_e64 v17, v22, v17, s[38:39]
	ds_bpermute_b32 v22, v9, v17
	v_add_f32_e32 v25, 1.0, v15
	s_waitcnt lgkmcnt(0)
	v_add_f32_e32 v22, v17, v22
	v_cndmask_b32_e64 v17, v22, v17, s[40:41]
	ds_bpermute_b32 v22, v10, v17
	s_waitcnt lgkmcnt(0)
	v_add_f32_e32 v22, v17, v22
	v_cndmask_b32_e64 v17, v22, v17, s[42:43]
	ds_bpermute_b32 v22, v11, v17
	s_waitcnt lgkmcnt(0)
	v_add_f32_e32 v22, v17, v22
	v_cndmask_b32_e64 v17, v22, v17, s[44:45]
	ds_bpermute_b32 v22, v12, v17
	s_waitcnt lgkmcnt(0)
	v_add_f32_e32 v22, v17, v22
	v_cndmask_b32_e64 v17, v22, v17, s[46:47]
	ds_bpermute_b32 v22, v13, v17
	s_waitcnt lgkmcnt(0)
; __device__ __forceinline__ float log_sigmoid(float x) { return fminf(x, 0.f) - log1pf(__expf(-fabsf(x))); }
; __device__ __forceinline__ void fox_cum_block(const bf16* PROJ, const float* fbias, float* CUM, int ci, LAS unsigned char* lds, int wave, int lane) {
;     ...
; #pragma unroll
;     for (int u = 0; u < 8; ++u) { float v = log_sigmoid(x[u] + bias);
; #pragma unroll
;         for (int o = 1; o < 64; o <<= 1) { const float y = __builtin_bit_cast(float, __builtin_amdgcn_ds_bpermute((lane - o) << 2, __builtin_bit_cast(int, v))); if (lane >= o) v += y; }
;         v += carry; vals[u] = v; carry = __builtin_bit_cast(float, __builtin_amdgcn_readlane(__builtin_bit_cast(int, v), 63)); }
	v_add_f32_e32 v22, v17, v22
	v_cndmask_b32_e64 v17, v22, v17, s[48:49]
	v_add_f32_e32 v22, -1.0, v25
	v_sub_f32_e32 v23, v22, v25
	v_add_f32_e32 v23, 1.0, v23
	v_sub_f32_e32 v22, v15, v22
	v_add_f32_e32 v26, v22, v23
	v_frexp_mant_f32_e32 v22, v25
	v_cmp_gt_f32_e32 vcc, s4, v22
	v_cvt_f64_f32_e32 v[22:23], v25
	v_frexp_exp_i32_f64_e32 v22, v[22:23]
	v_subbrev_co_u32_e32 v22, vcc, 0, v22, vcc
	v_sub_u32_e32 v23, 0, v22
	v_ldexp_f32 v25, v25, v23
	v_ldexp_f32 v23, v26, v23
	v_add_f32_e32 v26, -1.0, v25
	v_add_f32_e32 v27, 1.0, v26
	v_sub_f32_e32 v27, v25, v27
	v_add_f32_e32 v27, v23, v27
	v_add_f32_e32 v28, v26, v27
	v_sub_f32_e32 v26, v28, v26
	v_sub_f32_e32 v26, v27, v26
	v_add_f32_e32 v27, 1.0, v25
	v_add_f32_e32 v29, -1.0, v27
	v_sub_f32_e32 v25, v25, v29
	v_add_f32_e32 v23, v23, v25
	v_add_f32_e32 v25, v27, v23
	v_sub_f32_e32 v27, v25, v27
	v_sub_f32_e32 v23, v23, v27
	v_rcp_f32_e32 v27, v25
	v_cvt_f32_i32_e32 v22, v22
	v_cmp_neq_f32_e32 vcc, s11, v15
	v_add_f32_e32 v17, s2, v17
	v_mul_f32_e32 v29, v28, v27
	v_mul_f32_e32 v30, v25, v29
	v_fma_f32 v31, v29, v25, -v30
	v_fmac_f32_e32 v31, v29, v23
	v_add_f32_e32 v32, v30, v31
	v_sub_f32_e32 v33, v28, v32
	v_sub_f32_e32 v28, v28, v33
	v_sub_f32_e32 v30, v32, v30
	v_sub_f32_e32 v28, v28, v32
	v_add_f32_e32 v26, v26, v28
	v_sub_f32_e32 v28, v30, v31
	v_add_f32_e32 v26, v28, v26
	v_add_f32_e32 v28, v33, v26
	v_mul_f32_e32 v30, v27, v28
	v_mul_f32_e32 v31, v25, v30
	v_fma_f32 v25, v30, v25, -v31
	v_fmac_f32_e32 v25, v30, v23
	v_sub_f32_e32 v23, v33, v28
	v_add_f32_e32 v23, v26, v23
	v_add_f32_e32 v26, v31, v25
	v_sub_f32_e32 v32, v28, v26
	v_sub_f32_e32 v28, v28, v32
	v_sub_f32_e32 v31, v26, v31
	v_sub_f32_e32 v26, v28, v26
	v_add_f32_e32 v23, v23, v26
	v_sub_f32_e32 v25, v31, v25
	v_add_f32_e32 v23, v25, v23
	v_add_f32_e32 v25, v29, v30
	v_add_f32_e32 v23, v32, v23
	v_sub_f32_e32 v26, v25, v29
	v_mul_f32_e32 v23, v27, v23
	v_sub_f32_e32 v26, v30, v26
	v_add_f32_e32 v23, v26, v23
	v_mul_f32_e32 v29, 0x3f317218, v22
	v_add_f32_e32 v26, v25, v23
	v_fma_f32 v30, v22, s10, -v29
	v_mul_f32_e32 v27, v26, v26
	v_fmac_f32_e32 v30, 0xb102e308, v22
	v_sub_f32_e32 v22, v26, v25
	v_fmamk_f32 v28, v27, 0x3e9b6dac, v34
	v_sub_f32_e32 v22, v23, v22
	v_add_f32_e32 v23, v29, v30
	v_fmaak_f32 v28, v27, v28, 0x3f2aaada
	v_sub_f32_e32 v25, v23, v29
	v_ldexp_f32 v29, v26, 1
	v_mul_f32_e32 v26, v26, v27
	v_mul_f32_e32 v26, v26, v28
	v_add_f32_e32 v27, v29, v26
	v_sub_f32_e32 v28, v27, v29
	v_ldexp_f32 v22, v22, 1
	v_sub_f32_e32 v26, v26, v28
	v_add_f32_e32 v22, v22, v26
	v_add_f32_e32 v26, v27, v22
	v_sub_f32_e32 v27, v26, v27
	v_sub_f32_e32 v22, v22, v27
	v_add_f32_e32 v27, v23, v26
	v_sub_f32_e32 v28, v27, v23
	v_sub_f32_e32 v29, v27, v28
	v_sub_f32_e32 v25, v30, v25
	v_sub_f32_e32 v23, v23, v29
	v_sub_f32_e32 v26, v26, v28
	v_add_f32_e32 v23, v26, v23
	v_add_f32_e32 v26, v25, v22
	v_sub_f32_e32 v28, v26, v25
	v_sub_f32_e32 v29, v26, v28
	v_sub_f32_e32 v25, v25, v29
	v_sub_f32_e32 v22, v22, v28
	v_add_f32_e32 v23, v26, v23
	v_add_f32_e32 v22, v22, v25
	v_add_f32_e32 v25, v27, v23
	v_sub_f32_e32 v26, v25, v27
	v_sub_f32_e32 v23, v23, v26
	v_add_f32_e32 v22, v22, v23
	v_add_f32_e32 v22, v25, v22
	v_cndmask_b32_e32 v22, v230, v22, vcc
	v_cmp_ngt_f32_e32 vcc, -1.0, v15
	v_readlane_b32 s2, v17, 63
	s_nop 0
	v_cndmask_b32_e32 v22, v35, v22, vcc
	v_cmp_neq_f32_e32 vcc, -1.0, v15
	s_nop 1
	v_cndmask_b32_e32 v22, v234, v22, vcc
	v_cmp_lt_f32_e64 vcc, |v15|, s12
	s_nop 1
	v_cndmask_b32_e32 v15, v22, v15, vcc
	v_sub_f32_e32 v15, v24, v15
	ds_bpermute_b32 v22, v8, v15
	v_add_f32_e32 v24, 1.0, v2
	s_waitcnt lgkmcnt(0)
	v_add_f32_e32 v22, v15, v22
	v_cndmask_b32_e64 v15, v22, v15, s[38:39]
	ds_bpermute_b32 v22, v9, v15
	s_waitcnt lgkmcnt(0)
	v_add_f32_e32 v22, v15, v22
	v_cndmask_b32_e64 v15, v22, v15, s[40:41]
	ds_bpermute_b32 v22, v10, v15
	s_waitcnt lgkmcnt(0)
	v_add_f32_e32 v22, v15, v22
	v_cndmask_b32_e64 v15, v22, v15, s[42:43]
	ds_bpermute_b32 v22, v11, v15
	s_waitcnt lgkmcnt(0)
	v_add_f32_e32 v22, v15, v22
	v_cndmask_b32_e64 v15, v22, v15, s[44:45]
	ds_bpermute_b32 v22, v12, v15
	s_waitcnt lgkmcnt(0)
	v_add_f32_e32 v22, v15, v22
	v_cndmask_b32_e64 v15, v22, v15, s[46:47]
	ds_bpermute_b32 v22, v13, v15
	s_waitcnt lgkmcnt(0)
; #define LAS __attribute__((address_space(3)))
; __device__ __forceinline__ float log_sigmoid(float x) { return fminf(x, 0.f) - log1pf(__expf(-fabsf(x))); }
; __device__ __forceinline__ void fox_cum_block(const bf16* PROJ, const float* fbias, float* CUM, int ci, LAS unsigned char* lds, int wave, int lane) {
;     ...
; #pragma unroll
;     for (int u = 0; u < 8; ++u) { float v = log_sigmoid(x[u] + bias);
; #pragma unroll
;         for (int o = 1; o < 64; o <<= 1) { const float y = __builtin_bit_cast(float, __builtin_amdgcn_ds_bpermute((lane - o) << 2, __builtin_bit_cast(int, v))); if (lane >= o) v += y; }
;         v += carry; vals[u] = v; carry = __builtin_bit_cast(float, __builtin_amdgcn_readlane(__builtin_bit_cast(int, v), 63)); }
;     LAS float* tot = (LAS float*)lds;
;     if (lane == 0) tot[wave] = carry;
;     __syncthreads();
	v_add_f32_e32 v22, v15, v22
	v_cndmask_b32_e64 v15, v22, v15, s[48:49]
	v_add_f32_e32 v22, -1.0, v24
	v_sub_f32_e32 v23, v22, v24
	v_add_f32_e32 v23, 1.0, v23
	v_sub_f32_e32 v22, v2, v22
	v_add_f32_e32 v25, v22, v23
	v_frexp_mant_f32_e32 v22, v24
	v_cmp_gt_f32_e32 vcc, s4, v22
	v_cvt_f64_f32_e32 v[22:23], v24
	v_frexp_exp_i32_f64_e32 v22, v[22:23]
	v_subbrev_co_u32_e32 v22, vcc, 0, v22, vcc
	v_sub_u32_e32 v23, 0, v22
	v_ldexp_f32 v24, v24, v23
	v_ldexp_f32 v23, v25, v23
	v_add_f32_e32 v25, -1.0, v24
	v_add_f32_e32 v26, 1.0, v25
	v_sub_f32_e32 v26, v24, v26
	v_add_f32_e32 v26, v23, v26
	v_add_f32_e32 v27, v25, v26
	v_sub_f32_e32 v25, v27, v25
	v_sub_f32_e32 v25, v26, v25
	v_add_f32_e32 v26, 1.0, v24
	v_add_f32_e32 v28, -1.0, v26
	v_sub_f32_e32 v24, v24, v28
	v_add_f32_e32 v23, v23, v24
	v_add_f32_e32 v24, v26, v23
	v_sub_f32_e32 v26, v24, v26
	v_sub_f32_e32 v23, v23, v26
	v_rcp_f32_e32 v26, v24
	v_cvt_f32_i32_e32 v22, v22
	v_cmp_neq_f32_e32 vcc, s11, v2
	v_add_f32_e32 v15, s2, v15
	v_mul_f32_e32 v28, v27, v26
	v_mul_f32_e32 v29, v24, v28
	v_fma_f32 v30, v28, v24, -v29
	v_fmac_f32_e32 v30, v28, v23
	v_add_f32_e32 v31, v29, v30
	v_sub_f32_e32 v32, v27, v31
	v_sub_f32_e32 v27, v27, v32
	v_sub_f32_e32 v29, v31, v29
	v_sub_f32_e32 v27, v27, v31
	v_add_f32_e32 v25, v25, v27
	v_sub_f32_e32 v27, v29, v30
	v_add_f32_e32 v25, v27, v25
	v_add_f32_e32 v27, v32, v25
	v_mul_f32_e32 v29, v26, v27
	v_mul_f32_e32 v30, v24, v29
	v_fma_f32 v24, v29, v24, -v30
	v_fmac_f32_e32 v24, v29, v23
	v_sub_f32_e32 v23, v32, v27
	v_add_f32_e32 v23, v25, v23
	v_add_f32_e32 v25, v30, v24
	v_sub_f32_e32 v31, v27, v25
	v_sub_f32_e32 v27, v27, v31
	v_sub_f32_e32 v30, v25, v30
	v_sub_f32_e32 v25, v27, v25
	v_add_f32_e32 v23, v23, v25
	v_sub_f32_e32 v24, v30, v24
	v_add_f32_e32 v23, v24, v23
	v_add_f32_e32 v24, v28, v29
	v_add_f32_e32 v23, v31, v23
	v_sub_f32_e32 v25, v24, v28
	v_mul_f32_e32 v23, v26, v23
	v_sub_f32_e32 v25, v29, v25
	v_add_f32_e32 v23, v25, v23
	v_mul_f32_e32 v28, 0x3f317218, v22
	v_add_f32_e32 v25, v24, v23
	v_fma_f32 v29, v22, s10, -v28
	v_mul_f32_e32 v26, v25, v25
	v_fmac_f32_e32 v29, 0xb102e308, v22
	v_sub_f32_e32 v22, v25, v24
	v_fmamk_f32 v27, v26, 0x3e9b6dac, v34
	v_sub_f32_e32 v22, v23, v22
	v_add_f32_e32 v23, v28, v29
	v_fmaak_f32 v27, v26, v27, 0x3f2aaada
	v_sub_f32_e32 v24, v23, v28
	v_ldexp_f32 v28, v25, 1
	v_mul_f32_e32 v25, v25, v26
	v_mul_f32_e32 v25, v25, v27
	v_add_f32_e32 v26, v28, v25
	v_sub_f32_e32 v27, v26, v28
	v_ldexp_f32 v22, v22, 1
	v_sub_f32_e32 v25, v25, v27
	v_add_f32_e32 v22, v22, v25
	v_add_f32_e32 v25, v26, v22
	v_sub_f32_e32 v26, v25, v26
	v_sub_f32_e32 v22, v22, v26
	v_add_f32_e32 v26, v23, v25
	v_sub_f32_e32 v27, v26, v23
	v_sub_f32_e32 v28, v26, v27
	v_sub_f32_e32 v24, v29, v24
	v_sub_f32_e32 v23, v23, v28
	v_sub_f32_e32 v25, v25, v27
	v_add_f32_e32 v23, v25, v23
	v_add_f32_e32 v25, v24, v22
	v_sub_f32_e32 v27, v25, v24
	v_sub_f32_e32 v28, v25, v27
	v_sub_f32_e32 v24, v24, v28
	v_sub_f32_e32 v22, v22, v27
	v_add_f32_e32 v23, v25, v23
	v_add_f32_e32 v22, v22, v24
	v_add_f32_e32 v24, v26, v23
	v_sub_f32_e32 v25, v24, v26
	v_sub_f32_e32 v23, v23, v25
	v_add_f32_e32 v22, v22, v23
	v_add_f32_e32 v22, v24, v22
	v_cndmask_b32_e32 v22, v230, v22, vcc
	v_cmp_ngt_f32_e32 vcc, -1.0, v2
	v_readlane_b32 s2, v15, 63
	s_nop 0
	v_cndmask_b32_e32 v22, v35, v22, vcc
	v_cmp_neq_f32_e32 vcc, -1.0, v2
	s_nop 1
	v_cndmask_b32_e32 v22, v234, v22, vcc
	v_cmp_lt_f32_e64 vcc, |v2|, s12
	s_nop 1
	v_cndmask_b32_e32 v2, v22, v2, vcc
	v_sub_f32_e32 v2, v14, v2
	ds_bpermute_b32 v14, v8, v2
	s_waitcnt lgkmcnt(0)
	v_add_f32_e32 v14, v2, v14
	v_cndmask_b32_e64 v2, v14, v2, s[38:39]
	ds_bpermute_b32 v14, v9, v2
	s_waitcnt lgkmcnt(0)
	v_add_f32_e32 v14, v2, v14
	v_cndmask_b32_e64 v2, v14, v2, s[40:41]
	ds_bpermute_b32 v14, v10, v2
	s_waitcnt lgkmcnt(0)
	v_add_f32_e32 v14, v2, v14
	v_cndmask_b32_e64 v2, v14, v2, s[42:43]
	ds_bpermute_b32 v14, v11, v2
	s_waitcnt lgkmcnt(0)
	v_add_f32_e32 v14, v2, v14
	v_cndmask_b32_e64 v2, v14, v2, s[44:45]
	ds_bpermute_b32 v14, v12, v2
	s_waitcnt lgkmcnt(0)
	v_add_f32_e32 v14, v2, v14
	v_cndmask_b32_e64 v2, v14, v2, s[46:47]
	ds_bpermute_b32 v14, v13, v2
	s_waitcnt lgkmcnt(0)
	v_add_f32_e32 v14, v2, v14
	v_cndmask_b32_e64 v2, v14, v2, s[48:49]
	v_add_f32_e32 v2, s2, v2
	s_nop 0
	v_readlane_b32 s4, v2, 63
	s_and_saveexec_b64 s[2:3], s[38:39]
	v_mov_b32_e32 v14, s6
	v_mov_b32_e32 v22, s4
	ds_write_b32 v14, v22
	s_or_b64 exec, exec, s[2:3]
	s_andn2_b64 vcc, exec, s[16:17]
	s_waitcnt lgkmcnt(0)
	s_barrier
	s_cbranch_vccnz .LBB0_437
	s_mov_b32 s2, 0
	v_mov_b32_e32 v14, 0
	s_mov_b32 s3, s24

; __device__ __forceinline__ float wave_sum(float v) { v += lx<1>(v); v += lx<2>(v); v += lx<4>(v); v += lx<8>(v); v += lx<16>(v); return half_sum(v); }
; __device__ __forceinline__ void norm_final_rows(const bf16* src, const float* gain, float* dst, int gw, int NGW, int lane) {
;     for (int m = gw; m < M; m += NGW) {
;         const v4u* xr = (const v4u*)(src + (size_t)m * DM) + lane; f32x4 v[8]; float ss = 0.f;
; #pragma unroll
;         for (int j = 0; j < 4; ++j) { const v4u c = xr[64 * j]; v[2 * j] = (f32x4){lo16(c.x), hi16(c.x), lo16(c.y), hi16(c.y)}; v[2 * j + 1] = (f32x4){lo16(c.z), hi16(c.z), lo16(c.w), hi16(c.w)}; }
; #pragma unroll
;         for (int j = 0; j < 8; ++j) ss += (v[j].x * v[j].x + v[j].y * v[j].y) + (v[j].z * v[j].z + v[j].w * v[j].w);
;         const float rstd = rsqrtf(wave_sum(ss) * (1.f / DM) + 1e-6f);
;         float* o = dst + (size_t)m * DM;
; #pragma unroll
;         for (int j = 0; j < 4; ++j)
; #pragma unroll
;             for (int h = 0; h < 2; ++h) { const int col = 8 * (64 * j + lane) + 4 * h; const f32x4 g4 = *(const f32x4*)(gain + col); *(f32x4*)(o + col) = v[2 * j + h] * rstd * g4; }
.LBB0_2287:
	s_cmp_lt_i32 s68, 38
	s_cselect_b64 s[2:3], -1, 0
	s_cmp_gt_i32 s67, 37
	s_cselect_b64 s[4:5], -1, 0
	s_and_b64 s[2:3], s[2:3], s[4:5]
	s_and_b64 vcc, exec, s[2:3]
	s_cbranch_vccz .LBB0_2291
	s_load_dword s10, s[72:73], 0x0
	s_waitcnt lgkmcnt(0)
	v_readfirstlane_b32 s2, v0
	s_ashr_i32 s9, s2, 6
	s_load_dwordx2 s[4:5], s[0:1], 0x98
	s_load_dwordx2 s[6:7], s[0:1], 0x88
	s_load_dwordx2 s[2:3], s[0:1], 0x90
	s_lshl_b32 s1, s66, 3
	s_add_i32 s8, s1, s9
	s_cmpk_gt_i32 s8, 0x1fff
	s_cbranch_scc1 .LBB0_2291
	v_and_b32_e32 v14, 63, v0
	v_lshlrev_b32_e32 v10, 5, v14
	v_or_b32_e32 v12, 0x1800, v10
	v_mov_b32_e32 v13, 0
	s_waitcnt lgkmcnt(0)
	v_lshl_add_u64 v[0:1], s[6:7], 0, v[12:13]
	v_or_b32_e32 v12, 0x1000, v10
	v_lshl_add_u64 v[4:5], s[6:7], 0, v[12:13]
	v_or_b32_e32 v12, 0x1010, v10
	v_mov_b32_e32 v11, v13
	v_lshl_add_u64 v[6:7], s[6:7], 0, v[12:13]
	v_or_b32_e32 v12, 0x1810, v10
	s_lshl_b32 s0, s10, 3
	v_lshl_add_u64 v[2:3], s[6:7], 0, v[10:11]
	v_lshl_add_u64 v[8:9], s[6:7], 0, v[12:13]
	s_ashr_i32 s7, s9, 31
	s_ashr_i32 s10, s1, 31
	s_add_u32 s6, s9, s1
	s_addc_u32 s7, s7, s10
	s_lshl_b64 s[10:11], s[6:7], 13
	s_add_u32 s2, s2, s10
	s_addc_u32 s3, s3, s11
	v_lshl_add_u64 v[10:11], s[2:3], 0, v[10:11]
	s_mov_b64 s[2:3], 0x1000
	s_ashr_i32 s1, s0, 31
	v_lshl_add_u64 v[10:11], v[10:11], 0, s[2:3]
	s_lshl_b64 s[2:3], s[0:1], 13
	s_lshl_b64 s[6:7], s[6:7], 12
	s_add_u32 s4, s4, s6
	v_lshlrev_b32_e32 v12, 4, v14
	s_addc_u32 s5, s5, s7
	v_lshl_add_u64 v[12:13], s[4:5], 0, v[12:13]
	s_mov_b64 s[4:5], 0x4800000
	v_lshl_add_u64 v[12:13], v[12:13], 0, s[4:5]
	s_lshl_b64 s[4:5], s[0:1], 12
	v_mov_b32_e32 v22, 0x358637bd
	s_mov_b32 s1, 0x800000
	s_movk_i32 s6, 0xf000
	s_movk_i32 s7, 0xf010
	s_movk_i32 s9, 0xf800
	s_movk_i32 s10, 0xf810
	flat_load_dwordx4 v[64:67], v[2:3]
	flat_load_dwordx4 v[68:71], v[2:3] offset:16
	flat_load_dwordx4 v[72:75], v[2:3] offset:2048
	flat_load_dwordx4 v[76:79], v[2:3] offset:2064
	flat_load_dwordx4 v[80:83], v[4:5]
	flat_load_dwordx4 v[84:87], v[6:7]
	flat_load_dwordx4 v[88:91], v[0:1]
	flat_load_dwordx4 v[92:95], v[8:9]
; __device__ __forceinline__ float wave_sum(float v) { v += lx<1>(v); v += lx<2>(v); v += lx<4>(v); v += lx<8>(v); v += lx<16>(v); return half_sum(v); }
; __device__ __forceinline__ void norm_final_rows(const bf16* src, const float* gain, float* dst, int gw, int NGW, int lane) {
;     for (int m = gw; m < M; m += NGW) {
;         const v4u* xr = (const v4u*)(src + (size_t)m * DM) + lane; f32x4 v[8]; float ss = 0.f;
; #pragma unroll
;         for (int j = 0; j < 4; ++j) { const v4u c = xr[64 * j]; v[2 * j] = (f32x4){lo16(c.x), hi16(c.x), lo16(c.y), hi16(c.y)}; v[2 * j + 1] = (f32x4){lo16(c.z), hi16(c.z), lo16(c.w), hi16(c.w)}; }
; #pragma unroll
;         for (int j = 0; j < 8; ++j) ss += (v[j].x * v[j].x + v[j].y * v[j].y) + (v[j].z * v[j].z + v[j].w * v[j].w);
;         const float rstd = rsqrtf(wave_sum(ss) * (1.f / DM) + 1e-6f);
;         float* o = dst + (size_t)m * DM;
; #pragma unroll
;         for (int j = 0; j < 4; ++j)
; #pragma unroll
;             for (int h = 0; h < 2; ++h) { const int col = 8 * (64 * j + lane) + 4 * h; const f32x4 g4 = *(const f32x4*)(gain + col); *(f32x4*)(o + col) = v[2 * j + h] * rstd * g4; }
.LBB0_2290:
	flat_load_dwordx4 v[14:17], v[12:13]
	flat_load_dwordx4 v[18:21], v[12:13] offset:1024
	flat_load_dwordx4 v[24:27], v[12:13] offset:2048
	flat_load_dwordx4 v[28:31], v[12:13] offset:3072
	s_add_i32 s8, s8, s0
	v_lshl_add_u64 v[12:13], v[12:13], 0, s[4:5]
	s_cmpk_lt_i32 s8, 0x2000
	s_waitcnt vmcnt(0) lgkmcnt(0)
	v_and_b32_e32 v33, 0xffff0000, v14
	v_and_b32_e32 v35, 0xffff0000, v15
	v_and_b32_e32 v37, 0xffff0000, v16
	v_and_b32_e32 v39, 0xffff0000, v17
	v_lshlrev_b32_e32 v32, 16, v14
	v_lshlrev_b32_e32 v34, 16, v15
	v_lshlrev_b32_e32 v36, 16, v16
	v_lshlrev_b32_e32 v38, 16, v17
	v_and_b32_e32 v41, 0xffff0000, v18
	v_and_b32_e32 v43, 0xffff0000, v19
	v_lshlrev_b32_e32 v48, 16, v24
	v_and_b32_e32 v49, 0xffff0000, v24
	v_lshlrev_b32_e32 v50, 16, v25
	v_and_b32_e32 v51, 0xffff0000, v25
	v_lshlrev_b32_e32 v52, 16, v26
	v_and_b32_e32 v53, 0xffff0000, v26
	v_mul_f32_e32 v23, v33, v33
	v_mul_f32_e32 v24, v35, v35
	v_mul_f32_e32 v25, v37, v37
	v_mul_f32_e32 v26, v39, v39
	v_lshlrev_b32_e32 v40, 16, v18
	v_lshlrev_b32_e32 v42, 16, v19
	v_and_b32_e32 v45, 0xffff0000, v20
	v_and_b32_e32 v47, 0xffff0000, v21
	v_lshlrev_b32_e32 v54, 16, v27
	v_and_b32_e32 v55, 0xffff0000, v27
	v_lshlrev_b32_e32 v18, 16, v28
	v_and_b32_e32 v19, 0xffff0000, v28
	v_mul_f32_e32 v27, v41, v41
	v_mul_f32_e32 v28, v43, v43
	v_fmac_f32_e32 v23, v32, v32
	v_fmac_f32_e32 v24, v34, v34
	v_fmac_f32_e32 v25, v36, v36
	v_fmac_f32_e32 v26, v38, v38
	v_lshlrev_b32_e32 v44, 16, v20
	v_lshlrev_b32_e32 v46, 16, v21
	v_lshlrev_b32_e32 v20, 16, v29
	v_and_b32_e32 v21, 0xffff0000, v29
	v_lshlrev_b32_e32 v14, 16, v30
	v_and_b32_e32 v15, 0xffff0000, v30
	v_mul_f32_e32 v29, v45, v45
	v_mul_f32_e32 v30, v47, v47
	v_fmac_f32_e32 v27, v40, v40
	v_fmac_f32_e32 v28, v42, v42
	v_add_f32_e32 v23, v23, v24
	v_add_f32_e32 v24, v25, v26
	v_lshlrev_b32_e32 v16, 16, v31
	v_and_b32_e32 v17, 0xffff0000, v31
	v_mul_f32_e32 v31, v49, v49
	v_mul_f32_e32 v56, v51, v51
	v_fmac_f32_e32 v29, v44, v44
	v_fmac_f32_e32 v30, v46, v46
	v_add_f32_e32 v25, v27, v28
	v_add_f32_e32 v23, v23, v24
	v_mul_f32_e32 v57, v53, v53
	v_mul_f32_e32 v58, v55, v55
	v_fmac_f32_e32 v31, v48, v48
	v_fmac_f32_e32 v56, v50, v50
	v_add_f32_e32 v26, v29, v30
	v_add_f32_e32 v23, v23, v25
	v_mul_f32_e32 v59, v19, v19
	v_mul_f32_e32 v60, v21, v21
	v_fmac_f32_e32 v57, v52, v52
	v_fmac_f32_e32 v58, v54, v54
	v_add_f32_e32 v27, v31, v56
	v_add_f32_e32 v23, v26, v23
	v_mul_f32_e32 v61, v15, v15
	v_mul_f32_e32 v62, v17, v17
	v_fmac_f32_e32 v59, v18, v18
	v_fmac_f32_e32 v60, v20, v20
	v_add_f32_e32 v28, v57, v58
	v_add_f32_e32 v23, v27, v23
	v_fmac_f32_e32 v61, v14, v14
	v_fmac_f32_e32 v62, v16, v16
	v_add_f32_e32 v29, v59, v60
	v_add_f32_e32 v23, v28, v23
	v_add_f32_e32 v30, v61, v62
	v_add_f32_e32 v23, v29, v23
	v_add_f32_e32 v23, v30, v23
	ds_swizzle_b32 v24, v23 offset:swizzle(SWAP,1)
	v_add_co_u32_e32 v28, vcc, s6, v10
	s_waitcnt lgkmcnt(0)
	v_add_f32_e32 v23, v23, v24
	ds_swizzle_b32 v24, v23 offset:swizzle(SWAP,2)
	v_addc_co_u32_e32 v29, vcc, -1, v11, vcc
	s_waitcnt lgkmcnt(0)
	v_add_f32_e32 v23, v23, v24
	ds_swizzle_b32 v24, v23 offset:swizzle(SWAP,4)
	s_waitcnt lgkmcnt(0)
	v_add_f32_e32 v23, v23, v24
	ds_swizzle_b32 v24, v23 offset:swizzle(SWAP,8)
	s_waitcnt lgkmcnt(0)
	v_add_f32_e32 v23, v23, v24
	ds_swizzle_b32 v24, v23 offset:swizzle(SWAP,16)
	s_waitcnt lgkmcnt(0)
	v_add_f32_e32 v23, v23, v24
	v_mov_b32_e32 v30, v23
	s_nop 0
	v_permlane32_swap_b32_e32 v23, v30
	v_add_f32_e32 v23, v23, v30
	v_fmamk_f32 v23, v23, 0x3a000000, v22
	v_mul_f32_e32 v30, 0x4b800000, v23
	v_cmp_gt_f32_e32 vcc, s1, v23
	s_nop 1
	v_cndmask_b32_e32 v23, v23, v30, vcc
	v_rsq_f32_e32 v23, v23
	s_nop 0
	v_mul_f32_e32 v30, 0x45800000, v23
	v_cndmask_b32_e32 v30, v23, v30, vcc
	v_pk_mul_f32 v[32:33], v[32:33], v[30:31] op_sel_hi:[1,0]
	v_pk_mul_f32 v[34:35], v[34:35], v[30:31] op_sel_hi:[1,0]
	v_pk_mul_f32 v[20:21], v[20:21], v[30:31] op_sel_hi:[1,0]
	v_pk_mul_f32 v[18:19], v[18:19], v[30:31] op_sel_hi:[1,0]
	v_pk_mul_f32 v[16:17], v[16:17], v[30:31] op_sel_hi:[1,0]
	v_pk_mul_f32 v[14:15], v[14:15], v[30:31] op_sel_hi:[1,0]
	v_pk_mul_f32 v[26:27], v[66:67], v[34:35]
	v_pk_mul_f32 v[24:25], v[64:65], v[32:33]
	flat_store_dwordx4 v[28:29], v[24:27]
	v_add_co_u32_e32 v28, vcc, s7, v10
	v_pk_mul_f32 v[32:33], v[38:39], v[30:31] op_sel_hi:[1,0]
	v_pk_mul_f32 v[34:35], v[36:37], v[30:31] op_sel_hi:[1,0]
	v_addc_co_u32_e32 v29, vcc, -1, v11, vcc
	v_pk_mul_f32 v[24:25], v[68:69], v[34:35]
	v_pk_mul_f32 v[26:27], v[70:71], v[32:33]
	flat_store_dwordx4 v[28:29], v[24:27]
	v_add_co_u32_e32 v28, vcc, s9, v10
	v_pk_mul_f32 v[32:33], v[42:43], v[30:31] op_sel_hi:[1,0]
	v_pk_mul_f32 v[34:35], v[40:41], v[30:31] op_sel_hi:[1,0]
	v_addc_co_u32_e32 v29, vcc, -1, v11, vcc
	v_pk_mul_f32 v[24:25], v[72:73], v[34:35]
	v_pk_mul_f32 v[26:27], v[74:75], v[32:33]
	flat_store_dwordx4 v[28:29], v[24:27]
	v_add_co_u32_e32 v28, vcc, s10, v10
	v_pk_mul_f32 v[32:33], v[46:47], v[30:31] op_sel_hi:[1,0]
	v_pk_mul_f32 v[34:35], v[44:45], v[30:31] op_sel_hi:[1,0]
	v_addc_co_u32_e32 v29, vcc, -1, v11, vcc
	v_pk_mul_f32 v[24:25], v[76:77], v[34:35]
	v_pk_mul_f32 v[26:27], v[78:79], v[32:33]
	flat_store_dwordx4 v[28:29], v[24:27]
	v_pk_mul_f32 v[28:29], v[50:51], v[30:31] op_sel_hi:[1,0]
	v_pk_mul_f32 v[32:33], v[48:49], v[30:31] op_sel_hi:[1,0]
	v_pk_mul_f32 v[26:27], v[82:83], v[28:29]
	v_pk_mul_f32 v[24:25], v[80:81], v[32:33]
	flat_store_dwordx4 v[10:11], v[24:27]
	v_pk_mul_f32 v[28:29], v[54:55], v[30:31] op_sel_hi:[1,0]
	v_pk_mul_f32 v[32:33], v[52:53], v[30:31] op_sel_hi:[1,0]
	v_pk_mul_f32 v[26:27], v[86:87], v[28:29]
	v_pk_mul_f32 v[24:25], v[84:85], v[32:33]
	flat_store_dwordx4 v[10:11], v[24:27] offset:16
	v_pk_mul_f32 v[18:19], v[18:19], v[88:89]
	v_pk_mul_f32 v[20:21], v[20:21], v[90:91]
	flat_store_dwordx4 v[10:11], v[18:21] offset:2048
	v_pk_mul_f32 v[14:15], v[14:15], v[92:93]
	v_pk_mul_f32 v[16:17], v[16:17], v[94:95]
	flat_store_dwordx4 v[10:11], v[14:17] offset:2064
	v_lshl_add_u64 v[10:11], v[10:11], 0, s[2:3]
	s_cbranch_scc1 .LBB0_2290
